# K-loops (5 phases): the two A-operand LDS-DMA pieces of each SP2 load segment issued between the two MFMA blocks instead; vmcnt(8)->(6) at those waits
# baseline (speedup 1.0000x reference)
; #define PG8_STAGE(bufoff, gbase, voff) do { _Pragma("unroll") for (int _i = 0; _i < 2; ++_i) \
;         __builtin_amdgcn_global_load_lds((const unsigned*)((const char*)(gbase) + (voff)[_i]), (PG8_LAS unsigned*)(lds + (bufoff) + ldsw + _i * 8192), 16, 0, 0); } while (0)
; #define PG8_LDA(dst, b, h) do { _Pragma("unroll") for (int m = 0; m < 4; ++m) _Pragma("unroll") for (int k = 0; k < 2; ++k) dst[m][k] = *(const PG8_LAS bf16x8*)(lds + PG8_SA(b, h) + aoff + m * 2048 + k * 1024); } while (0)
; #define PG8_LDB(dst, b, h) do { _Pragma("unroll") for (int n = 0; n < 2; ++n) _Pragma("unroll") for (int k = 0; k < 2; ++k) dst[n][k] = *(const PG8_LAS bf16x8*)(lds + PG8_SB(b, h) + boff + n * 2048 + k * 1024); } while (0)
; #define PG8_MMA(ai, bj, At, Bt) do { __builtin_amdgcn_s_setprio(1); _Pragma("unroll") for (int m = 0; m < 4; ++m) _Pragma("unroll") for (int n = 0; n < 2; ++n) _Pragma("unroll") for (int k = 0; k < 2; ++k) \
;         acc[ai][bj][m][n] = __builtin_amdgcn_mfma_f32_16x16x32_bf16(Bt[n][k], At[m][k], acc[ai][bj][m][n], 0, 0, 0); __builtin_amdgcn_s_setprio(0); } while (0)
; #define PG8_WAIT_V(n) asm volatile("s_waitcnt vmcnt(" #n ")" ::: "memory")
; #define PG8_WAIT_L(n) asm volatile("s_waitcnt lgkmcnt(" #n ")" ::: "memory")
; #define PG8_BAR __builtin_amdgcn_s_barrier()
; #define PG8_SCHED __builtin_amdgcn_sched_barrier(0)
; template <class Epi, class Sched, bool ALIGN_EPI = false, bool SP2 = false>
; __device__ __forceinline__ void gemm_phase(PG8_LAS unsigned char* lds, const Gemm g, const Sched& S, const Epi& E) {
;     ...
;             PG8_LDB(B0, 0, 0); PG8_LDB(B1, 0, 1); PG8_SCHED; PG8_LDA(At, 0, 0); PG8_STAGE(PG8_SA(1, 1), a1 + hstep, voffA);
;             PG8_WAIT_V(8); PG8_WAIT_L(0); PG8_BAR; PG8_MMA(0, 0, At, B0); PG8_MMA(0, 1, At, B1); PG8_BAR; PG8_SCHED;
;             PG8_LDA(At, 0, 1); PG8_STAGE(PG8_SB(0, 0), b2, voffB); PG8_STAGE(PG8_SB(0, 1), b2 + hstep, voffB); PG8_STAGE(PG8_SA(0, 0), a2, voffA);
;             PG8_WAIT_V(8); PG8_WAIT_L(0); PG8_BAR; PG8_MMA(1, 0, At, B0); PG8_MMA(1, 1, At, B1); PG8_BAR; PG8_SCHED;
.LBB0_121:
	ds_read_b128 v[128:131], v173
	ds_read_b128 v[132:135], v173 offset:1024
	ds_read_b128 v[136:139], v173 offset:2048
	ds_read_b128 v[140:143], v173 offset:3072
	ds_read_b128 v[144:147], v175
	ds_read_b128 v[148:151], v175 offset:1024
	ds_read_b128 v[184:187], v175 offset:2048
	ds_read_b128 v[188:191], v175 offset:3072
	s_add_u32 s6, s4, 0xfffc0080
	s_addc_u32 s7, s5, -1
	s_cmp_eq_u32 s27, 12
	s_cselect_b32 s9, s1, s7
	s_cselect_b32 s8, s10, s6
	s_cselect_b32 s7, s11, s25
	s_cselect_b32 s6, s16, s24
	v_lshl_add_u64 v[192:193], s[4:5], 0, v[176:177]
	s_add_i32 m0, s37, 0xc000
	ds_read_b128 v[202:205], v194
	ds_read_b128 v[206:209], v194 offset:1024
	ds_read_b128 v[210:213], v194 offset:2048
	ds_read_b128 v[214:217], v194 offset:3072
	ds_read_b128 v[218:221], v194 offset:4096
	ds_read_b128 v[222:225], v194 offset:5120
	ds_read_b128 v[230:233], v194 offset:6144
	ds_read_b128 v[234:237], v194 offset:7168
	global_load_lds_dwordx4 v[192:193], off
	v_lshl_add_u64 v[192:193], s[4:5], 0, v[178:179]
	s_add_i32 m0, s37, 0xe000
	s_nop 0
	global_load_lds_dwordx4 v[192:193], off
	s_waitcnt vmcnt(8)
	s_waitcnt lgkmcnt(0)
	s_barrier
	s_setprio 1
	s_waitcnt lgkmcnt(0)
	v_mfma_f32_16x16x32_bf16 v[124:127], v[128:131], v[202:205], v[124:127]
	v_mfma_f32_16x16x32_bf16 v[120:123], v[136:139], v[202:205], v[120:123]
	v_mfma_f32_16x16x32_bf16 v[108:111], v[128:131], v[210:213], v[108:111]
	v_mfma_f32_16x16x32_bf16 v[104:107], v[136:139], v[210:213], v[104:107]
	v_mfma_f32_16x16x32_bf16 v[92:95], v[128:131], v[218:221], v[92:95]
	v_mfma_f32_16x16x32_bf16 v[88:91], v[136:139], v[218:221], v[88:91]
	v_mfma_f32_16x16x32_bf16 v[76:79], v[128:131], v[230:233], v[76:79]
	v_mfma_f32_16x16x32_bf16 v[72:75], v[136:139], v[230:233], v[72:75]
	v_mfma_f32_16x16x32_bf16 v[124:127], v[132:135], v[206:209], v[124:127]
	v_mfma_f32_16x16x32_bf16 v[120:123], v[140:143], v[206:209], v[120:123]
	v_mfma_f32_16x16x32_bf16 v[108:111], v[132:135], v[214:217], v[108:111]
	v_mfma_f32_16x16x32_bf16 v[104:107], v[140:143], v[214:217], v[104:107]
	v_mfma_f32_16x16x32_bf16 v[92:95], v[132:135], v[222:225], v[92:95]
	v_mfma_f32_16x16x32_bf16 v[88:91], v[140:143], v[222:225], v[88:91]
	v_mfma_f32_16x16x32_bf16 v[76:79], v[132:135], v[234:237], v[76:79]
	v_mfma_f32_16x16x32_bf16 v[72:75], v[140:143], v[234:237], v[72:75]
	s_setprio 0
	s_setprio 1
	v_mfma_f32_16x16x32_bf16 v[116:119], v[144:147], v[202:205], v[116:119]
	v_mfma_f32_16x16x32_bf16 v[112:115], v[184:187], v[202:205], v[112:115]
	v_mfma_f32_16x16x32_bf16 v[100:103], v[144:147], v[210:213], v[100:103]
	v_mfma_f32_16x16x32_bf16 v[96:99], v[184:187], v[210:213], v[96:99]
	v_mfma_f32_16x16x32_bf16 v[84:87], v[144:147], v[218:221], v[84:87]
	v_mfma_f32_16x16x32_bf16 v[80:83], v[184:187], v[218:221], v[80:83]
	v_mfma_f32_16x16x32_bf16 v[68:71], v[144:147], v[230:233], v[68:71]
	v_mfma_f32_16x16x32_bf16 v[64:67], v[184:187], v[230:233], v[64:67]
	v_mfma_f32_16x16x32_bf16 v[116:119], v[148:151], v[206:209], v[116:119]
	v_mfma_f32_16x16x32_bf16 v[112:115], v[188:191], v[206:209], v[112:115]
	v_mfma_f32_16x16x32_bf16 v[100:103], v[148:151], v[214:217], v[100:103]
	v_mfma_f32_16x16x32_bf16 v[96:99], v[188:191], v[214:217], v[96:99]
	v_mfma_f32_16x16x32_bf16 v[84:87], v[148:151], v[222:225], v[84:87]
	v_mfma_f32_16x16x32_bf16 v[80:83], v[188:191], v[222:225], v[80:83]
	v_mfma_f32_16x16x32_bf16 v[68:71], v[148:151], v[234:237], v[68:71]
	v_mfma_f32_16x16x32_bf16 v[64:67], v[188:191], v[234:237], v[64:67]
	s_setprio 0
	s_barrier
	s_add_i32 s29, s33, s74
	v_lshl_add_u64 v[192:193], s[6:7], 0, v[158:159]
	s_mov_b32 m0, s29
	ds_read_b128 v[202:205], v194 offset:16384
	ds_read_b128 v[206:209], v194 offset:17408
	ds_read_b128 v[210:213], v194 offset:18432
	ds_read_b128 v[214:217], v194 offset:19456
	ds_read_b128 v[218:221], v194 offset:20480
	ds_read_b128 v[222:225], v194 offset:21504
	ds_read_b128 v[230:233], v194 offset:22528
	ds_read_b128 v[234:237], v194 offset:23552
	global_load_lds_dwordx4 v[192:193], off
	s_add_i32 m0, s29, 0x2000
	s_add_u32 s38, s6, 0x40000
	v_lshl_add_u64 v[238:239], s[6:7], 0, v[162:163]
	s_addc_u32 s39, s7, 0
	s_add_i32 s29, s83, s74
	global_load_lds_dwordx4 v[238:239], off
	v_lshl_add_u64 v[240:241], s[38:39], 0, v[158:159]
	s_mov_b32 m0, s29
	v_lshl_add_u64 v[242:243], s[8:9], 0, v[160:161]
	global_load_lds_dwordx4 v[240:241], off
	v_lshl_add_u64 v[240:241], s[38:39], 0, v[162:163]
	s_add_i32 m0, s29, 0x2000
	s_nop 0
	global_load_lds_dwordx4 v[240:241], off
	s_waitcnt vmcnt(6)
	s_waitcnt lgkmcnt(0)
	s_barrier
; #define PG8_STAGE(bufoff, gbase, voff) do { _Pragma("unroll") for (int _i = 0; _i < 2; ++_i) \
;         __builtin_amdgcn_global_load_lds((const unsigned*)((const char*)(gbase) + (voff)[_i]), (PG8_LAS unsigned*)(lds + (bufoff) + ldsw + _i * 8192), 16, 0, 0); } while (0)
; #define PG8_LDA(dst, b, h) do { _Pragma("unroll") for (int m = 0; m < 4; ++m) _Pragma("unroll") for (int k = 0; k < 2; ++k) dst[m][k] = *(const PG8_LAS bf16x8*)(lds + PG8_SA(b, h) + aoff + m * 2048 + k * 1024); } while (0)
; #define PG8_LDB(dst, b, h) do { _Pragma("unroll") for (int n = 0; n < 2; ++n) _Pragma("unroll") for (int k = 0; k < 2; ++k) dst[n][k] = *(const PG8_LAS bf16x8*)(lds + PG8_SB(b, h) + boff + n * 2048 + k * 1024); } while (0)
; #define PG8_MMA(ai, bj, At, Bt) do { __builtin_amdgcn_s_setprio(1); _Pragma("unroll") for (int m = 0; m < 4; ++m) _Pragma("unroll") for (int n = 0; n < 2; ++n) _Pragma("unroll") for (int k = 0; k < 2; ++k) \
;         acc[ai][bj][m][n] = __builtin_amdgcn_mfma_f32_16x16x32_bf16(Bt[n][k], At[m][k], acc[ai][bj][m][n], 0, 0, 0); __builtin_amdgcn_s_setprio(0); } while (0)
; #define PG8_WAIT_V(n) asm volatile("s_waitcnt vmcnt(" #n ")" ::: "memory")
; #define PG8_WAIT_L(n) asm volatile("s_waitcnt lgkmcnt(" #n ")" ::: "memory")
; #define PG8_BAR __builtin_amdgcn_s_barrier()
; #define PG8_SCHED __builtin_amdgcn_sched_barrier(0)
; template <class Epi, class Sched, bool ALIGN_EPI = false, bool SP2 = false>
; __device__ __forceinline__ void gemm_phase(PG8_LAS unsigned char* lds, const Gemm g, const Sched& S, const Epi& E) {
;     ...
;             PG8_WAIT_V(8); PG8_WAIT_L(0); PG8_BAR; PG8_MMA(1, 0, At, B0); PG8_MMA(1, 1, At, B1); PG8_BAR; PG8_SCHED;
;             PG8_LDB(B0, 1, 0); PG8_LDB(B1, 1, 1); PG8_SCHED; PG8_LDA(At, 1, 0); PG8_STAGE(PG8_SA(0, 1), a2 + hstep, voffA);
;             PG8_WAIT_V(8); PG8_WAIT_L(0); PG8_BAR; PG8_MMA(0, 0, At, B0); PG8_MMA(0, 1, At, B1); PG8_BAR; PG8_SCHED;
	s_setprio 1
	s_waitcnt lgkmcnt(0)
	v_mfma_f32_16x16x32_bf16 v[60:63], v[128:131], v[202:205], v[60:63]
	v_mfma_f32_16x16x32_bf16 v[56:59], v[136:139], v[202:205], v[56:59]
	v_mfma_f32_16x16x32_bf16 v[44:47], v[128:131], v[210:213], v[44:47]
	v_mfma_f32_16x16x32_bf16 v[40:43], v[136:139], v[210:213], v[40:43]
	v_mfma_f32_16x16x32_bf16 v[28:31], v[128:131], v[218:221], v[28:31]
	v_mfma_f32_16x16x32_bf16 v[24:27], v[136:139], v[218:221], v[24:27]
	v_mfma_f32_16x16x32_bf16 v[12:15], v[128:131], v[230:233], v[12:15]
	v_mfma_f32_16x16x32_bf16 v[8:11], v[136:139], v[230:233], v[8:11]
	v_mfma_f32_16x16x32_bf16 v[60:63], v[132:135], v[206:209], v[60:63]
	v_mfma_f32_16x16x32_bf16 v[56:59], v[140:143], v[206:209], v[56:59]
	v_mfma_f32_16x16x32_bf16 v[44:47], v[132:135], v[214:217], v[44:47]
	v_mfma_f32_16x16x32_bf16 v[40:43], v[140:143], v[214:217], v[40:43]
	v_mfma_f32_16x16x32_bf16 v[28:31], v[132:135], v[222:225], v[28:31]
	v_mfma_f32_16x16x32_bf16 v[24:27], v[140:143], v[222:225], v[24:27]
	v_mfma_f32_16x16x32_bf16 v[12:15], v[132:135], v[234:237], v[12:15]
	v_mfma_f32_16x16x32_bf16 v[8:11], v[140:143], v[234:237], v[8:11]
	s_setprio 0
	v_lshl_add_u64 v[240:241], s[8:9], 0, v[156:157]
	s_mov_b32 m0, s37
	s_nop 0
	global_load_lds_dwordx4 v[240:241], off
	s_mov_b32 m0, s75
	s_nop 0
	global_load_lds_dwordx4 v[242:243], off
	s_setprio 1
	v_mfma_f32_16x16x32_bf16 v[52:55], v[144:147], v[202:205], v[52:55]
	v_mfma_f32_16x16x32_bf16 v[48:51], v[184:187], v[202:205], v[48:51]
	v_mfma_f32_16x16x32_bf16 v[36:39], v[144:147], v[210:213], v[36:39]
	v_mfma_f32_16x16x32_bf16 v[32:35], v[184:187], v[210:213], v[32:35]
	v_mfma_f32_16x16x32_bf16 v[20:23], v[144:147], v[218:221], v[20:23]
	v_mfma_f32_16x16x32_bf16 v[16:19], v[184:187], v[218:221], v[16:19]
	v_mfma_f32_16x16x32_bf16 v[4:7], v[144:147], v[230:233], v[4:7]
	v_mfma_f32_16x16x32_bf16 v[0:3], v[184:187], v[230:233], v[0:3]
	v_mfma_f32_16x16x32_bf16 v[52:55], v[148:151], v[206:209], v[52:55]
	v_mfma_f32_16x16x32_bf16 v[48:51], v[188:191], v[206:209], v[48:51]
	v_mfma_f32_16x16x32_bf16 v[36:39], v[148:151], v[214:217], v[36:39]
	v_mfma_f32_16x16x32_bf16 v[32:35], v[188:191], v[214:217], v[32:35]
	v_mfma_f32_16x16x32_bf16 v[20:23], v[148:151], v[222:225], v[20:23]
	v_mfma_f32_16x16x32_bf16 v[16:19], v[188:191], v[222:225], v[16:19]
	v_mfma_f32_16x16x32_bf16 v[4:7], v[148:151], v[234:237], v[4:7]
	v_mfma_f32_16x16x32_bf16 v[0:3], v[188:191], v[234:237], v[0:3]
	s_setprio 0
	s_barrier
	s_add_i32 s29, 0, 0x18000
	s_add_i32 s38, 0, 0x1c000
	v_add_u32_e32 v140, s29, v169
	v_add_u32_e32 v164, s38, v169
	ds_read_b128 v[128:131], v140
	ds_read_b128 v[132:135], v140 offset:1024
	ds_read_b128 v[136:139], v140 offset:2048
	ds_read_b128 v[140:143], v140 offset:3072
	ds_read_b128 v[144:147], v164
	ds_read_b128 v[148:151], v164 offset:1024
	ds_read_b128 v[184:187], v164 offset:2048
	ds_read_b128 v[188:191], v164 offset:3072
	s_add_u32 s8, s8, 0x40000
	s_addc_u32 s9, s9, 0
	s_mov_b32 m0, s76
	v_lshl_add_u64 v[244:245], s[8:9], 0, v[156:157]
	ds_read_b128 v[202:205], v194 offset:32768
	ds_read_b128 v[206:209], v194 offset:33792
	ds_read_b128 v[210:213], v194 offset:34816
	ds_read_b128 v[214:217], v194 offset:35840
	ds_read_b128 v[218:221], v194 offset:36864
	ds_read_b128 v[222:225], v194 offset:37888
	ds_read_b128 v[230:233], v194 offset:38912
	ds_read_b128 v[234:237], v194 offset:39936
	global_load_lds_dwordx4 v[244:245], off
	v_lshl_add_u64 v[244:245], s[8:9], 0, v[160:161]
	s_mov_b32 m0, s77
	s_nop 0
	global_load_lds_dwordx4 v[244:245], off
	s_waitcnt vmcnt(8)
	s_waitcnt lgkmcnt(0)
	s_barrier
	s_setprio 1
	s_waitcnt lgkmcnt(0)
	v_mfma_f32_16x16x32_bf16 v[124:127], v[128:131], v[202:205], v[124:127]
	v_mfma_f32_16x16x32_bf16 v[120:123], v[136:139], v[202:205], v[120:123]
	v_mfma_f32_16x16x32_bf16 v[108:111], v[128:131], v[210:213], v[108:111]
	v_mfma_f32_16x16x32_bf16 v[104:107], v[136:139], v[210:213], v[104:107]
	v_mfma_f32_16x16x32_bf16 v[92:95], v[128:131], v[218:221], v[92:95]
	v_mfma_f32_16x16x32_bf16 v[88:91], v[136:139], v[218:221], v[88:91]
	v_mfma_f32_16x16x32_bf16 v[76:79], v[128:131], v[230:233], v[76:79]
	v_mfma_f32_16x16x32_bf16 v[72:75], v[136:139], v[230:233], v[72:75]
	v_mfma_f32_16x16x32_bf16 v[124:127], v[132:135], v[206:209], v[124:127]
	v_mfma_f32_16x16x32_bf16 v[120:123], v[140:143], v[206:209], v[120:123]
	v_mfma_f32_16x16x32_bf16 v[108:111], v[132:135], v[214:217], v[108:111]
	v_mfma_f32_16x16x32_bf16 v[104:107], v[140:143], v[214:217], v[104:107]
	v_mfma_f32_16x16x32_bf16 v[92:95], v[132:135], v[222:225], v[92:95]
	v_mfma_f32_16x16x32_bf16 v[88:91], v[140:143], v[222:225], v[88:91]
	v_mfma_f32_16x16x32_bf16 v[76:79], v[132:135], v[234:237], v[76:79]
	v_mfma_f32_16x16x32_bf16 v[72:75], v[140:143], v[234:237], v[72:75]
	s_setprio 0
	s_setprio 1
	v_mfma_f32_16x16x32_bf16 v[116:119], v[144:147], v[202:205], v[116:119]
	v_mfma_f32_16x16x32_bf16 v[112:115], v[184:187], v[202:205], v[112:115]
	v_mfma_f32_16x16x32_bf16 v[100:103], v[144:147], v[210:213], v[100:103]
	v_mfma_f32_16x16x32_bf16 v[96:99], v[184:187], v[210:213], v[96:99]
	v_mfma_f32_16x16x32_bf16 v[84:87], v[144:147], v[218:221], v[84:87]
	v_mfma_f32_16x16x32_bf16 v[80:83], v[184:187], v[218:221], v[80:83]
	v_mfma_f32_16x16x32_bf16 v[68:71], v[144:147], v[230:233], v[68:71]
	v_mfma_f32_16x16x32_bf16 v[64:67], v[184:187], v[230:233], v[64:67]
	v_mfma_f32_16x16x32_bf16 v[116:119], v[148:151], v[206:209], v[116:119]
	v_mfma_f32_16x16x32_bf16 v[112:115], v[188:191], v[206:209], v[112:115]
	v_mfma_f32_16x16x32_bf16 v[100:103], v[148:151], v[214:217], v[100:103]
	v_mfma_f32_16x16x32_bf16 v[96:99], v[188:191], v[214:217], v[96:99]
	v_mfma_f32_16x16x32_bf16 v[84:87], v[148:151], v[222:225], v[84:87]
	v_mfma_f32_16x16x32_bf16 v[80:83], v[188:191], v[222:225], v[80:83]
	v_mfma_f32_16x16x32_bf16 v[68:71], v[148:151], v[234:237], v[68:71]
	v_mfma_f32_16x16x32_bf16 v[64:67], v[188:191], v[234:237], v[64:67]
	s_setprio 0
	s_barrier
; #define PG8_STAGE(bufoff, gbase, voff) do { _Pragma("unroll") for (int _i = 0; _i < 2; ++_i) \
;         __builtin_amdgcn_global_load_lds((const unsigned*)((const char*)(gbase) + (voff)[_i]), (PG8_LAS unsigned*)(lds + (bufoff) + ldsw + _i * 8192), 16, 0, 0); } while (0)
; #define PG8_LDA(dst, b, h) do { _Pragma("unroll") for (int m = 0; m < 4; ++m) _Pragma("unroll") for (int k = 0; k < 2; ++k) dst[m][k] = *(const PG8_LAS bf16x8*)(lds + PG8_SA(b, h) + aoff + m * 2048 + k * 1024); } while (0)
; #define PG8_MMA(ai, bj, At, Bt) do { __builtin_amdgcn_s_setprio(1); _Pragma("unroll") for (int m = 0; m < 4; ++m) _Pragma("unroll") for (int n = 0; n < 2; ++n) _Pragma("unroll") for (int k = 0; k < 2; ++k) \
;         acc[ai][bj][m][n] = __builtin_amdgcn_mfma_f32_16x16x32_bf16(Bt[n][k], At[m][k], acc[ai][bj][m][n], 0, 0, 0); __builtin_amdgcn_s_setprio(0); } while (0)
; #define PG8_WAIT_V(n) asm volatile("s_waitcnt vmcnt(" #n ")" ::: "memory")
; #define PG8_WAIT_L(n) asm volatile("s_waitcnt lgkmcnt(" #n ")" ::: "memory")
; #define PG8_BAR __builtin_amdgcn_s_barrier()
; #define PG8_SCHED __builtin_amdgcn_sched_barrier(0)
; template <class Epi, class Sched, bool ALIGN_EPI = false, bool SP2 = false>
; __device__ __forceinline__ void gemm_phase(PG8_LAS unsigned char* lds, const Gemm g, const Sched& S, const Epi& E) {
;     ...
;             PG8_LDA(At, 1, 1); PG8_STAGE(PG8_SB(1, 0), b3, voffB); PG8_STAGE(PG8_SB(1, 1), b3 + hstep, voffB); PG8_STAGE(PG8_SA(1, 0), a3, voffA);
;             PG8_WAIT_V(8); PG8_WAIT_L(0); PG8_BAR; PG8_MMA(1, 0, At, B0); PG8_MMA(1, 1, At, B1); PG8_BAR; PG8_SCHED;
	s_add_i32 s8, s29, s74
	v_lshl_add_u64 v[192:193], v[192:193], 0, s[22:23]
	s_mov_b32 m0, s8
	ds_read_b128 v[202:205], v194 offset:49152
	ds_read_b128 v[206:209], v194 offset:50176
	ds_read_b128 v[210:213], v194 offset:51200
	ds_read_b128 v[214:217], v194 offset:52224
	ds_read_b128 v[218:221], v194 offset:53248
	ds_read_b128 v[222:225], v194 offset:54272
	ds_read_b128 v[230:233], v194 offset:55296
	ds_read_b128 v[234:237], v194 offset:56320
	global_load_lds_dwordx4 v[192:193], off
	s_add_i32 m0, s8, 0x2000
	s_add_u32 s6, s6, 0x40080
	v_lshl_add_u64 v[192:193], v[238:239], 0, s[22:23]
	s_addc_u32 s7, s7, 0
	s_add_i32 s8, s38, s74
	global_load_lds_dwordx4 v[192:193], off
	v_lshl_add_u64 v[192:193], s[6:7], 0, v[158:159]
	s_mov_b32 m0, s8
	s_nop 0
	global_load_lds_dwordx4 v[192:193], off
	v_lshl_add_u64 v[192:193], s[6:7], 0, v[162:163]
	s_add_i32 m0, s8, 0x2000
	s_nop 0
	global_load_lds_dwordx4 v[192:193], off
	s_waitcnt vmcnt(6)
	s_waitcnt lgkmcnt(0)
	s_barrier
	s_setprio 1
	s_waitcnt lgkmcnt(0)
	v_mfma_f32_16x16x32_bf16 v[60:63], v[128:131], v[202:205], v[60:63]
	v_mfma_f32_16x16x32_bf16 v[56:59], v[136:139], v[202:205], v[56:59]
	v_mfma_f32_16x16x32_bf16 v[44:47], v[128:131], v[210:213], v[44:47]
	v_mfma_f32_16x16x32_bf16 v[40:43], v[136:139], v[210:213], v[40:43]
	v_mfma_f32_16x16x32_bf16 v[28:31], v[128:131], v[218:221], v[28:31]
	v_mfma_f32_16x16x32_bf16 v[24:27], v[136:139], v[218:221], v[24:27]
	v_mfma_f32_16x16x32_bf16 v[12:15], v[128:131], v[230:233], v[12:15]
	v_mfma_f32_16x16x32_bf16 v[8:11], v[136:139], v[230:233], v[8:11]
	v_mfma_f32_16x16x32_bf16 v[60:63], v[132:135], v[206:209], v[60:63]
	v_mfma_f32_16x16x32_bf16 v[56:59], v[140:143], v[206:209], v[56:59]
	v_mfma_f32_16x16x32_bf16 v[44:47], v[132:135], v[214:217], v[44:47]
	v_mfma_f32_16x16x32_bf16 v[40:43], v[140:143], v[214:217], v[40:43]
	v_mfma_f32_16x16x32_bf16 v[28:31], v[132:135], v[222:225], v[28:31]
	v_mfma_f32_16x16x32_bf16 v[24:27], v[140:143], v[222:225], v[24:27]
	v_mfma_f32_16x16x32_bf16 v[12:15], v[132:135], v[234:237], v[12:15]
	v_mfma_f32_16x16x32_bf16 v[8:11], v[140:143], v[234:237], v[8:11]
	s_setprio 0
	v_lshl_add_u64 v[192:193], v[240:241], 0, s[22:23]
	s_mov_b32 m0, s95
	s_nop 0
	global_load_lds_dwordx4 v[192:193], off
	v_lshl_add_u64 v[192:193], v[242:243], 0, s[22:23]
	s_mov_b32 m0, s96
	s_nop 0
	global_load_lds_dwordx4 v[192:193], off
	s_setprio 1
	v_mfma_f32_16x16x32_bf16 v[52:55], v[144:147], v[202:205], v[52:55]
	v_mfma_f32_16x16x32_bf16 v[48:51], v[184:187], v[202:205], v[48:51]
	v_mfma_f32_16x16x32_bf16 v[36:39], v[144:147], v[210:213], v[36:39]
	v_mfma_f32_16x16x32_bf16 v[32:35], v[184:187], v[210:213], v[32:35]
	v_mfma_f32_16x16x32_bf16 v[20:23], v[144:147], v[218:221], v[20:23]
	v_mfma_f32_16x16x32_bf16 v[16:19], v[184:187], v[218:221], v[16:19]
	v_mfma_f32_16x16x32_bf16 v[4:7], v[144:147], v[230:233], v[4:7]
	v_mfma_f32_16x16x32_bf16 v[0:3], v[184:187], v[230:233], v[0:3]
	v_mfma_f32_16x16x32_bf16 v[52:55], v[148:151], v[206:209], v[52:55]
	v_mfma_f32_16x16x32_bf16 v[48:51], v[188:191], v[206:209], v[48:51]
	v_mfma_f32_16x16x32_bf16 v[36:39], v[148:151], v[214:217], v[36:39]
	v_mfma_f32_16x16x32_bf16 v[32:35], v[188:191], v[214:217], v[32:35]
	v_mfma_f32_16x16x32_bf16 v[20:23], v[148:151], v[222:225], v[20:23]
	v_mfma_f32_16x16x32_bf16 v[16:19], v[188:191], v[222:225], v[16:19]
	v_mfma_f32_16x16x32_bf16 v[4:7], v[148:151], v[234:237], v[4:7]
	v_mfma_f32_16x16x32_bf16 v[0:3], v[188:191], v[234:237], v[0:3]
	s_setprio 0
	s_barrier
	s_add_i32 s27, s27, 2
	s_add_u32 s4, s4, 0x100
	s_addc_u32 s5, s5, 0
	s_add_u32 s24, s24, 0x100
	s_addc_u32 s25, s25, 0
	s_cmp_gt_u32 s27, 13
	s_cbranch_scc0 .LBB0_121
	s_and_b64 vcc, exec, s[70:71]
	s_cbranch_vccz .LBB0_124
	s_barrier

; #define PG8_STAGE(bufoff, gbase, voff) do { _Pragma("unroll") for (int _i = 0; _i < 2; ++_i) \
;         __builtin_amdgcn_global_load_lds((const unsigned*)((const char*)(gbase) + (voff)[_i]), (PG8_LAS unsigned*)(lds + (bufoff) + ldsw + _i * 8192), 16, 0, 0); } while (0)
; #define PG8_LDA(dst, b, h) do { _Pragma("unroll") for (int m = 0; m < 4; ++m) _Pragma("unroll") for (int k = 0; k < 2; ++k) dst[m][k] = *(const PG8_LAS bf16x8*)(lds + PG8_SA(b, h) + aoff + m * 2048 + k * 1024); } while (0)
; #define PG8_LDB(dst, b, h) do { _Pragma("unroll") for (int n = 0; n < 2; ++n) _Pragma("unroll") for (int k = 0; k < 2; ++k) dst[n][k] = *(const PG8_LAS bf16x8*)(lds + PG8_SB(b, h) + boff + n * 2048 + k * 1024); } while (0)
; #define PG8_MMA(ai, bj, At, Bt) do { __builtin_amdgcn_s_setprio(1); _Pragma("unroll") for (int m = 0; m < 4; ++m) _Pragma("unroll") for (int n = 0; n < 2; ++n) _Pragma("unroll") for (int k = 0; k < 2; ++k) \
;         acc[ai][bj][m][n] = __builtin_amdgcn_mfma_f32_16x16x32_bf16(Bt[n][k], At[m][k], acc[ai][bj][m][n], 0, 0, 0); __builtin_amdgcn_s_setprio(0); } while (0)
; #define PG8_WAIT_V(n) asm volatile("s_waitcnt vmcnt(" #n ")" ::: "memory")
; #define PG8_WAIT_L(n) asm volatile("s_waitcnt lgkmcnt(" #n ")" ::: "memory")
; #define PG8_BAR __builtin_amdgcn_s_barrier()
; #define PG8_SCHED __builtin_amdgcn_sched_barrier(0)
; template <class Epi, class Sched, bool ALIGN_EPI = false, bool SP2 = false>
; __device__ __forceinline__ void gemm_phase(PG8_LAS unsigned char* lds, const Gemm g, const Sched& S, const Epi& E) {
;     ...
;             PG8_LDB(B0, 0, 0); PG8_LDB(B1, 0, 1); PG8_SCHED; PG8_LDA(At, 0, 0); PG8_STAGE(PG8_SA(1, 1), a1 + hstep, voffA);
;             PG8_WAIT_V(8); PG8_WAIT_L(0); PG8_BAR; PG8_MMA(0, 0, At, B0); PG8_MMA(0, 1, At, B1); PG8_BAR; PG8_SCHED;
;             PG8_LDA(At, 0, 1); PG8_STAGE(PG8_SB(0, 0), b2, voffB); PG8_STAGE(PG8_SB(0, 1), b2 + hstep, voffB); PG8_STAGE(PG8_SA(0, 0), a2, voffA);
;             PG8_WAIT_V(8); PG8_WAIT_L(0); PG8_BAR; PG8_MMA(1, 0, At, B0); PG8_MMA(1, 1, At, B1); PG8_BAR; PG8_SCHED;
.LBB0_1284:
	ds_read_b128 v[144:147], v153
	ds_read_b128 v[156:159], v153 offset:1024
	ds_read_b128 v[160:163], v153 offset:2048
	ds_read_b128 v[164:167], v153 offset:3072
	ds_read_b128 v[168:171], v154
	ds_read_b128 v[172:175], v154 offset:1024
	ds_read_b128 v[176:179], v154 offset:2048
	ds_read_b128 v[180:183], v154 offset:3072
	s_add_u32 s38, s36, 0xfffe0080
	s_addc_u32 s39, s37, -1
	s_cmp_eq_u32 s74, 4
	s_cselect_b32 s41, s27, s39
	s_cselect_b32 s40, s70, s38
	s_cselect_b32 s39, s25, s73
	s_cselect_b32 s38, s71, s72
	v_lshl_add_u64 v[148:149], s[36:37], 0, v[136:137]
	s_add_i32 m0, s35, 0xc000
	ds_read_b128 v[184:187], v155
	ds_read_b128 v[188:191], v155 offset:1024
	ds_read_b128 v[192:195], v155 offset:2048
	ds_read_b128 v[196:199], v155 offset:3072
	ds_read_b128 v[200:203], v155 offset:4096
	ds_read_b128 v[204:207], v155 offset:5120
	ds_read_b128 v[208:211], v155 offset:6144
	ds_read_b128 v[212:215], v155 offset:7168
	global_load_lds_dwordx4 v[148:149], off
	v_lshl_add_u64 v[148:149], s[36:37], 0, v[138:139]
	s_add_i32 m0, s35, 0xe000
	s_nop 0
	global_load_lds_dwordx4 v[148:149], off
	s_waitcnt vmcnt(8)
	s_waitcnt lgkmcnt(0)
	s_barrier
	s_setprio 1
	s_waitcnt lgkmcnt(0)
	v_mfma_f32_16x16x32_bf16 v[124:127], v[144:147], v[184:187], v[124:127]
	v_mfma_f32_16x16x32_bf16 v[120:123], v[160:163], v[184:187], v[120:123]
	v_mfma_f32_16x16x32_bf16 v[112:115], v[144:147], v[192:195], v[112:115]
	v_mfma_f32_16x16x32_bf16 v[104:107], v[160:163], v[192:195], v[104:107]
	v_mfma_f32_16x16x32_bf16 v[96:99], v[144:147], v[200:203], v[96:99]
	v_mfma_f32_16x16x32_bf16 v[88:91], v[160:163], v[200:203], v[88:91]
	v_mfma_f32_16x16x32_bf16 v[80:83], v[144:147], v[208:211], v[80:83]
	v_mfma_f32_16x16x32_bf16 v[72:75], v[160:163], v[208:211], v[72:75]
	v_mfma_f32_16x16x32_bf16 v[124:127], v[156:159], v[188:191], v[124:127]
	v_mfma_f32_16x16x32_bf16 v[120:123], v[164:167], v[188:191], v[120:123]
	v_mfma_f32_16x16x32_bf16 v[112:115], v[156:159], v[196:199], v[112:115]
	v_mfma_f32_16x16x32_bf16 v[104:107], v[164:167], v[196:199], v[104:107]
	v_mfma_f32_16x16x32_bf16 v[96:99], v[156:159], v[204:207], v[96:99]
	v_mfma_f32_16x16x32_bf16 v[88:91], v[164:167], v[204:207], v[88:91]
	v_mfma_f32_16x16x32_bf16 v[80:83], v[156:159], v[212:215], v[80:83]
	v_mfma_f32_16x16x32_bf16 v[72:75], v[164:167], v[212:215], v[72:75]
	s_setprio 0
	s_setprio 1
	v_mfma_f32_16x16x32_bf16 v[116:119], v[168:171], v[184:187], v[116:119]
	v_mfma_f32_16x16x32_bf16 v[108:111], v[176:179], v[184:187], v[108:111]
	v_mfma_f32_16x16x32_bf16 v[100:103], v[168:171], v[192:195], v[100:103]
	v_mfma_f32_16x16x32_bf16 v[92:95], v[176:179], v[192:195], v[92:95]
	v_mfma_f32_16x16x32_bf16 v[84:87], v[168:171], v[200:203], v[84:87]
	v_mfma_f32_16x16x32_bf16 v[76:79], v[176:179], v[200:203], v[76:79]
	v_mfma_f32_16x16x32_bf16 v[68:71], v[168:171], v[208:211], v[68:71]
	v_mfma_f32_16x16x32_bf16 v[64:67], v[176:179], v[208:211], v[64:67]
	v_mfma_f32_16x16x32_bf16 v[116:119], v[172:175], v[188:191], v[116:119]
	v_mfma_f32_16x16x32_bf16 v[108:111], v[180:183], v[188:191], v[108:111]
	v_mfma_f32_16x16x32_bf16 v[100:103], v[172:175], v[196:199], v[100:103]
	v_mfma_f32_16x16x32_bf16 v[92:95], v[180:183], v[196:199], v[92:95]
	v_mfma_f32_16x16x32_bf16 v[84:87], v[172:175], v[204:207], v[84:87]
	v_mfma_f32_16x16x32_bf16 v[76:79], v[180:183], v[204:207], v[76:79]
	v_mfma_f32_16x16x32_bf16 v[68:71], v[172:175], v[212:215], v[68:71]
	v_mfma_f32_16x16x32_bf16 v[64:67], v[180:183], v[212:215], v[64:67]
	s_setprio 0
	s_barrier
	s_add_i32 s75, s67, s43
	v_lshl_add_u64 v[148:149], s[38:39], 0, v[132:133]
	s_mov_b32 m0, s75
	ds_read_b128 v[184:187], v155 offset:16384
	ds_read_b128 v[188:191], v155 offset:17408
	ds_read_b128 v[192:195], v155 offset:18432
	ds_read_b128 v[196:199], v155 offset:19456
	ds_read_b128 v[200:203], v155 offset:20480
	ds_read_b128 v[204:207], v155 offset:21504
	ds_read_b128 v[208:211], v155 offset:22528
	ds_read_b128 v[212:215], v155 offset:23552
	global_load_lds_dwordx4 v[148:149], off
	s_add_i32 m0, s75, 0x2000
	s_add_u32 s76, s38, 0x20000
	v_lshl_add_u64 v[216:217], s[38:39], 0, v[128:129]
	s_addc_u32 s77, s39, 0
	s_add_i32 s75, s68, s43
	global_load_lds_dwordx4 v[216:217], off
	v_lshl_add_u64 v[218:219], s[76:77], 0, v[132:133]
	s_mov_b32 m0, s75
	v_lshl_add_u64 v[220:221], s[40:41], 0, v[130:131]
	global_load_lds_dwordx4 v[218:219], off
	v_lshl_add_u64 v[218:219], s[76:77], 0, v[128:129]
	s_add_i32 m0, s75, 0x2000
	s_nop 0
	global_load_lds_dwordx4 v[218:219], off
	s_waitcnt vmcnt(6)
	s_waitcnt lgkmcnt(0)
	s_barrier
; #define PG8_STAGE(bufoff, gbase, voff) do { _Pragma("unroll") for (int _i = 0; _i < 2; ++_i) \
;         __builtin_amdgcn_global_load_lds((const unsigned*)((const char*)(gbase) + (voff)[_i]), (PG8_LAS unsigned*)(lds + (bufoff) + ldsw + _i * 8192), 16, 0, 0); } while (0)
; #define PG8_LDA(dst, b, h) do { _Pragma("unroll") for (int m = 0; m < 4; ++m) _Pragma("unroll") for (int k = 0; k < 2; ++k) dst[m][k] = *(const PG8_LAS bf16x8*)(lds + PG8_SA(b, h) + aoff + m * 2048 + k * 1024); } while (0)
; #define PG8_LDB(dst, b, h) do { _Pragma("unroll") for (int n = 0; n < 2; ++n) _Pragma("unroll") for (int k = 0; k < 2; ++k) dst[n][k] = *(const PG8_LAS bf16x8*)(lds + PG8_SB(b, h) + boff + n * 2048 + k * 1024); } while (0)
; #define PG8_MMA(ai, bj, At, Bt) do { __builtin_amdgcn_s_setprio(1); _Pragma("unroll") for (int m = 0; m < 4; ++m) _Pragma("unroll") for (int n = 0; n < 2; ++n) _Pragma("unroll") for (int k = 0; k < 2; ++k) \
;         acc[ai][bj][m][n] = __builtin_amdgcn_mfma_f32_16x16x32_bf16(Bt[n][k], At[m][k], acc[ai][bj][m][n], 0, 0, 0); __builtin_amdgcn_s_setprio(0); } while (0)
; #define PG8_WAIT_V(n) asm volatile("s_waitcnt vmcnt(" #n ")" ::: "memory")
; #define PG8_WAIT_L(n) asm volatile("s_waitcnt lgkmcnt(" #n ")" ::: "memory")
; #define PG8_BAR __builtin_amdgcn_s_barrier()
; #define PG8_SCHED __builtin_amdgcn_sched_barrier(0)
; template <class Epi, class Sched, bool ALIGN_EPI = false, bool SP2 = false>
; __device__ __forceinline__ void gemm_phase(PG8_LAS unsigned char* lds, const Gemm g, const Sched& S, const Epi& E) {
;     ...
;             PG8_WAIT_V(8); PG8_WAIT_L(0); PG8_BAR; PG8_MMA(1, 0, At, B0); PG8_MMA(1, 1, At, B1); PG8_BAR; PG8_SCHED;
;             PG8_LDB(B0, 1, 0); PG8_LDB(B1, 1, 1); PG8_SCHED; PG8_LDA(At, 1, 0); PG8_STAGE(PG8_SA(0, 1), a2 + hstep, voffA);
;             PG8_WAIT_V(8); PG8_WAIT_L(0); PG8_BAR; PG8_MMA(0, 0, At, B0); PG8_MMA(0, 1, At, B1); PG8_BAR; PG8_SCHED;
	s_setprio 1
	s_waitcnt lgkmcnt(0)
	v_mfma_f32_16x16x32_bf16 v[60:63], v[144:147], v[184:187], v[60:63]
	v_mfma_f32_16x16x32_bf16 v[56:59], v[160:163], v[184:187], v[56:59]
	v_mfma_f32_16x16x32_bf16 v[48:51], v[144:147], v[192:195], v[48:51]
	v_mfma_f32_16x16x32_bf16 v[40:43], v[160:163], v[192:195], v[40:43]
	v_mfma_f32_16x16x32_bf16 v[32:35], v[144:147], v[200:203], v[32:35]
	v_mfma_f32_16x16x32_bf16 v[24:27], v[160:163], v[200:203], v[24:27]
	v_mfma_f32_16x16x32_bf16 v[16:19], v[144:147], v[208:211], v[16:19]
	v_mfma_f32_16x16x32_bf16 v[8:11], v[160:163], v[208:211], v[8:11]
	v_mfma_f32_16x16x32_bf16 v[60:63], v[156:159], v[188:191], v[60:63]
	v_mfma_f32_16x16x32_bf16 v[56:59], v[164:167], v[188:191], v[56:59]
	v_mfma_f32_16x16x32_bf16 v[48:51], v[156:159], v[196:199], v[48:51]
	v_mfma_f32_16x16x32_bf16 v[40:43], v[164:167], v[196:199], v[40:43]
	v_mfma_f32_16x16x32_bf16 v[32:35], v[156:159], v[204:207], v[32:35]
	v_mfma_f32_16x16x32_bf16 v[24:27], v[164:167], v[204:207], v[24:27]
	v_mfma_f32_16x16x32_bf16 v[16:19], v[156:159], v[212:215], v[16:19]
	v_mfma_f32_16x16x32_bf16 v[8:11], v[164:167], v[212:215], v[8:11]
	s_setprio 0
	v_lshl_add_u64 v[218:219], s[40:41], 0, v[134:135]
	s_mov_b32 m0, s35
	s_nop 0
	global_load_lds_dwordx4 v[218:219], off
	s_mov_b32 m0, s52
	s_nop 0
	global_load_lds_dwordx4 v[220:221], off
	s_setprio 1
	v_mfma_f32_16x16x32_bf16 v[52:55], v[168:171], v[184:187], v[52:55]
	v_mfma_f32_16x16x32_bf16 v[44:47], v[176:179], v[184:187], v[44:47]
	v_mfma_f32_16x16x32_bf16 v[36:39], v[168:171], v[192:195], v[36:39]
	v_mfma_f32_16x16x32_bf16 v[28:31], v[176:179], v[192:195], v[28:31]
	v_mfma_f32_16x16x32_bf16 v[20:23], v[168:171], v[200:203], v[20:23]
	v_mfma_f32_16x16x32_bf16 v[12:15], v[176:179], v[200:203], v[12:15]
	v_mfma_f32_16x16x32_bf16 v[4:7], v[168:171], v[208:211], v[4:7]
	v_mfma_f32_16x16x32_bf16 v[0:3], v[176:179], v[208:211], v[0:3]
	v_mfma_f32_16x16x32_bf16 v[52:55], v[172:175], v[188:191], v[52:55]
	v_mfma_f32_16x16x32_bf16 v[44:47], v[180:183], v[188:191], v[44:47]
	v_mfma_f32_16x16x32_bf16 v[36:39], v[172:175], v[196:199], v[36:39]
	v_mfma_f32_16x16x32_bf16 v[28:31], v[180:183], v[196:199], v[28:31]
	v_mfma_f32_16x16x32_bf16 v[20:23], v[172:175], v[204:207], v[20:23]
	v_mfma_f32_16x16x32_bf16 v[12:15], v[180:183], v[204:207], v[12:15]
	v_mfma_f32_16x16x32_bf16 v[4:7], v[172:175], v[212:215], v[4:7]
	v_mfma_f32_16x16x32_bf16 v[0:3], v[180:183], v[212:215], v[0:3]
	s_setprio 0
	s_barrier
	s_add_i32 s75, 0, 0x18000
	s_add_i32 s76, 0, 0x1c000
	v_add_u32_e32 v164, s75, v151
	v_add_u32_e32 v180, s76, v151
	ds_read_b128 v[144:147], v164
	ds_read_b128 v[156:159], v164 offset:1024
	ds_read_b128 v[160:163], v164 offset:2048
	ds_read_b128 v[164:167], v164 offset:3072
	ds_read_b128 v[168:171], v180
	ds_read_b128 v[172:175], v180 offset:1024
	ds_read_b128 v[176:179], v180 offset:2048
	ds_read_b128 v[180:183], v180 offset:3072
	s_add_u32 s40, s40, 0x20000
	s_addc_u32 s41, s41, 0
	s_mov_b32 m0, s53
	v_lshl_add_u64 v[222:223], s[40:41], 0, v[134:135]
	ds_read_b128 v[184:187], v155 offset:32768
	ds_read_b128 v[188:191], v155 offset:33792
	ds_read_b128 v[192:195], v155 offset:34816
	ds_read_b128 v[196:199], v155 offset:35840
	ds_read_b128 v[200:203], v155 offset:36864
	ds_read_b128 v[204:207], v155 offset:37888
	ds_read_b128 v[208:211], v155 offset:38912
	ds_read_b128 v[212:215], v155 offset:39936
	global_load_lds_dwordx4 v[222:223], off
	v_lshl_add_u64 v[222:223], s[40:41], 0, v[130:131]
	s_mov_b32 m0, s60
	s_nop 0
	global_load_lds_dwordx4 v[222:223], off
	s_waitcnt vmcnt(8)
	s_waitcnt lgkmcnt(0)
	s_barrier
	s_setprio 1
	s_waitcnt lgkmcnt(0)
	v_mfma_f32_16x16x32_bf16 v[124:127], v[144:147], v[184:187], v[124:127]
	v_mfma_f32_16x16x32_bf16 v[120:123], v[160:163], v[184:187], v[120:123]
	v_mfma_f32_16x16x32_bf16 v[112:115], v[144:147], v[192:195], v[112:115]
	v_mfma_f32_16x16x32_bf16 v[104:107], v[160:163], v[192:195], v[104:107]
	v_mfma_f32_16x16x32_bf16 v[96:99], v[144:147], v[200:203], v[96:99]
	v_mfma_f32_16x16x32_bf16 v[88:91], v[160:163], v[200:203], v[88:91]
	v_mfma_f32_16x16x32_bf16 v[80:83], v[144:147], v[208:211], v[80:83]
	v_mfma_f32_16x16x32_bf16 v[72:75], v[160:163], v[208:211], v[72:75]
	v_mfma_f32_16x16x32_bf16 v[124:127], v[156:159], v[188:191], v[124:127]
	v_mfma_f32_16x16x32_bf16 v[120:123], v[164:167], v[188:191], v[120:123]
	v_mfma_f32_16x16x32_bf16 v[112:115], v[156:159], v[196:199], v[112:115]
	v_mfma_f32_16x16x32_bf16 v[104:107], v[164:167], v[196:199], v[104:107]
	v_mfma_f32_16x16x32_bf16 v[96:99], v[156:159], v[204:207], v[96:99]
	v_mfma_f32_16x16x32_bf16 v[88:91], v[164:167], v[204:207], v[88:91]
	v_mfma_f32_16x16x32_bf16 v[80:83], v[156:159], v[212:215], v[80:83]
	v_mfma_f32_16x16x32_bf16 v[72:75], v[164:167], v[212:215], v[72:75]
	s_setprio 0
	s_setprio 1
	v_mfma_f32_16x16x32_bf16 v[116:119], v[168:171], v[184:187], v[116:119]
	v_mfma_f32_16x16x32_bf16 v[108:111], v[176:179], v[184:187], v[108:111]
	v_mfma_f32_16x16x32_bf16 v[100:103], v[168:171], v[192:195], v[100:103]
	v_mfma_f32_16x16x32_bf16 v[92:95], v[176:179], v[192:195], v[92:95]
	v_mfma_f32_16x16x32_bf16 v[84:87], v[168:171], v[200:203], v[84:87]
	v_mfma_f32_16x16x32_bf16 v[76:79], v[176:179], v[200:203], v[76:79]
	v_mfma_f32_16x16x32_bf16 v[68:71], v[168:171], v[208:211], v[68:71]
	v_mfma_f32_16x16x32_bf16 v[64:67], v[176:179], v[208:211], v[64:67]
	v_mfma_f32_16x16x32_bf16 v[116:119], v[172:175], v[188:191], v[116:119]
	v_mfma_f32_16x16x32_bf16 v[108:111], v[180:183], v[188:191], v[108:111]
	v_mfma_f32_16x16x32_bf16 v[100:103], v[172:175], v[196:199], v[100:103]
	v_mfma_f32_16x16x32_bf16 v[92:95], v[180:183], v[196:199], v[92:95]
	v_mfma_f32_16x16x32_bf16 v[84:87], v[172:175], v[204:207], v[84:87]
	v_mfma_f32_16x16x32_bf16 v[76:79], v[180:183], v[204:207], v[76:79]
	v_mfma_f32_16x16x32_bf16 v[68:71], v[172:175], v[212:215], v[68:71]
	v_mfma_f32_16x16x32_bf16 v[64:67], v[180:183], v[212:215], v[64:67]
	s_setprio 0
	s_barrier
; #define PG8_STAGE(bufoff, gbase, voff) do { _Pragma("unroll") for (int _i = 0; _i < 2; ++_i) \
;         __builtin_amdgcn_global_load_lds((const unsigned*)((const char*)(gbase) + (voff)[_i]), (PG8_LAS unsigned*)(lds + (bufoff) + ldsw + _i * 8192), 16, 0, 0); } while (0)
; #define PG8_LDA(dst, b, h) do { _Pragma("unroll") for (int m = 0; m < 4; ++m) _Pragma("unroll") for (int k = 0; k < 2; ++k) dst[m][k] = *(const PG8_LAS bf16x8*)(lds + PG8_SA(b, h) + aoff + m * 2048 + k * 1024); } while (0)
; #define PG8_MMA(ai, bj, At, Bt) do { __builtin_amdgcn_s_setprio(1); _Pragma("unroll") for (int m = 0; m < 4; ++m) _Pragma("unroll") for (int n = 0; n < 2; ++n) _Pragma("unroll") for (int k = 0; k < 2; ++k) \
;         acc[ai][bj][m][n] = __builtin_amdgcn_mfma_f32_16x16x32_bf16(Bt[n][k], At[m][k], acc[ai][bj][m][n], 0, 0, 0); __builtin_amdgcn_s_setprio(0); } while (0)
; #define PG8_WAIT_V(n) asm volatile("s_waitcnt vmcnt(" #n ")" ::: "memory")
; #define PG8_WAIT_L(n) asm volatile("s_waitcnt lgkmcnt(" #n ")" ::: "memory")
; #define PG8_BAR __builtin_amdgcn_s_barrier()
; #define PG8_SCHED __builtin_amdgcn_sched_barrier(0)
; template <class Epi, class Sched, bool ALIGN_EPI = false, bool SP2 = false>
; __device__ __forceinline__ void gemm_phase(PG8_LAS unsigned char* lds, const Gemm g, const Sched& S, const Epi& E) {
;     ...
;             PG8_LDA(At, 1, 1); PG8_STAGE(PG8_SB(1, 0), b3, voffB); PG8_STAGE(PG8_SB(1, 1), b3 + hstep, voffB); PG8_STAGE(PG8_SA(1, 0), a3, voffA);
;             PG8_WAIT_V(8); PG8_WAIT_L(0); PG8_BAR; PG8_MMA(1, 0, At, B0); PG8_MMA(1, 1, At, B1); PG8_BAR; PG8_SCHED;
	s_add_i32 s40, s75, s43
	v_lshl_add_u64 v[148:149], v[148:149], 0, s[12:13]
	s_mov_b32 m0, s40
	ds_read_b128 v[184:187], v155 offset:49152
	ds_read_b128 v[188:191], v155 offset:50176
	ds_read_b128 v[192:195], v155 offset:51200
	ds_read_b128 v[196:199], v155 offset:52224
	ds_read_b128 v[200:203], v155 offset:53248
	ds_read_b128 v[204:207], v155 offset:54272
	ds_read_b128 v[208:211], v155 offset:55296
	ds_read_b128 v[212:215], v155 offset:56320
	global_load_lds_dwordx4 v[148:149], off
	s_add_i32 m0, s40, 0x2000
	s_add_u32 s38, s38, 0x20080
	v_lshl_add_u64 v[148:149], v[216:217], 0, s[12:13]
	s_addc_u32 s39, s39, 0
	s_add_i32 s40, s76, s43
	global_load_lds_dwordx4 v[148:149], off
	v_lshl_add_u64 v[148:149], s[38:39], 0, v[132:133]
	s_mov_b32 m0, s40
	s_nop 0
	global_load_lds_dwordx4 v[148:149], off
	v_lshl_add_u64 v[148:149], s[38:39], 0, v[128:129]
	s_add_i32 m0, s40, 0x2000
	s_nop 0
	global_load_lds_dwordx4 v[148:149], off
	s_waitcnt vmcnt(6)
	s_waitcnt lgkmcnt(0)
	s_barrier
	s_setprio 1
	s_waitcnt lgkmcnt(0)
	v_mfma_f32_16x16x32_bf16 v[60:63], v[144:147], v[184:187], v[60:63]
	v_mfma_f32_16x16x32_bf16 v[56:59], v[160:163], v[184:187], v[56:59]
	v_mfma_f32_16x16x32_bf16 v[48:51], v[144:147], v[192:195], v[48:51]
	v_mfma_f32_16x16x32_bf16 v[40:43], v[160:163], v[192:195], v[40:43]
	v_mfma_f32_16x16x32_bf16 v[32:35], v[144:147], v[200:203], v[32:35]
	v_mfma_f32_16x16x32_bf16 v[24:27], v[160:163], v[200:203], v[24:27]
	v_mfma_f32_16x16x32_bf16 v[16:19], v[144:147], v[208:211], v[16:19]
	v_mfma_f32_16x16x32_bf16 v[8:11], v[160:163], v[208:211], v[8:11]
	v_mfma_f32_16x16x32_bf16 v[60:63], v[156:159], v[188:191], v[60:63]
	v_mfma_f32_16x16x32_bf16 v[56:59], v[164:167], v[188:191], v[56:59]
	v_mfma_f32_16x16x32_bf16 v[48:51], v[156:159], v[196:199], v[48:51]
	v_mfma_f32_16x16x32_bf16 v[40:43], v[164:167], v[196:199], v[40:43]
	v_mfma_f32_16x16x32_bf16 v[32:35], v[156:159], v[204:207], v[32:35]
	v_mfma_f32_16x16x32_bf16 v[24:27], v[164:167], v[204:207], v[24:27]
	v_mfma_f32_16x16x32_bf16 v[16:19], v[156:159], v[212:215], v[16:19]
	v_mfma_f32_16x16x32_bf16 v[8:11], v[164:167], v[212:215], v[8:11]
	s_setprio 0
	v_lshl_add_u64 v[148:149], v[218:219], 0, s[12:13]
	s_mov_b32 m0, s64
	s_nop 0
	global_load_lds_dwordx4 v[148:149], off
	v_lshl_add_u64 v[148:149], v[220:221], 0, s[12:13]
	s_mov_b32 m0, s65
	s_nop 0
	global_load_lds_dwordx4 v[148:149], off
	s_setprio 1
	v_mfma_f32_16x16x32_bf16 v[52:55], v[168:171], v[184:187], v[52:55]
	v_mfma_f32_16x16x32_bf16 v[44:47], v[176:179], v[184:187], v[44:47]
	v_mfma_f32_16x16x32_bf16 v[36:39], v[168:171], v[192:195], v[36:39]
	v_mfma_f32_16x16x32_bf16 v[28:31], v[176:179], v[192:195], v[28:31]
	v_mfma_f32_16x16x32_bf16 v[20:23], v[168:171], v[200:203], v[20:23]
	v_mfma_f32_16x16x32_bf16 v[12:15], v[176:179], v[200:203], v[12:15]
	v_mfma_f32_16x16x32_bf16 v[4:7], v[168:171], v[208:211], v[4:7]
	v_mfma_f32_16x16x32_bf16 v[0:3], v[176:179], v[208:211], v[0:3]
	v_mfma_f32_16x16x32_bf16 v[52:55], v[172:175], v[188:191], v[52:55]
	v_mfma_f32_16x16x32_bf16 v[44:47], v[180:183], v[188:191], v[44:47]
	v_mfma_f32_16x16x32_bf16 v[36:39], v[172:175], v[196:199], v[36:39]
	v_mfma_f32_16x16x32_bf16 v[28:31], v[180:183], v[196:199], v[28:31]
	v_mfma_f32_16x16x32_bf16 v[20:23], v[172:175], v[204:207], v[20:23]
	v_mfma_f32_16x16x32_bf16 v[12:15], v[180:183], v[204:207], v[12:15]
	v_mfma_f32_16x16x32_bf16 v[4:7], v[172:175], v[212:215], v[4:7]
	v_mfma_f32_16x16x32_bf16 v[0:3], v[180:183], v[212:215], v[0:3]
	s_setprio 0
	s_barrier
	s_add_i32 s74, s74, 2
	s_add_u32 s36, s36, 0x100
	s_addc_u32 s37, s37, 0
	s_add_u32 s72, s72, 0x100
	s_addc_u32 s73, s73, 0
	s_cmp_gt_u32 s74, 5
	s_cbranch_scc0 .LBB0_1284
	s_and_b64 vcc, exec, s[14:15]
	s_cbranch_vccz .LBB0_1287
	s_barrier

; #define PG8_STAGE(bufoff, gbase, voff) do { _Pragma("unroll") for (int _i = 0; _i < 2; ++_i) \
;         __builtin_amdgcn_global_load_lds((const unsigned*)((const char*)(gbase) + (voff)[_i]), (PG8_LAS unsigned*)(lds + (bufoff) + ldsw + _i * 8192), 16, 0, 0); } while (0)
; #define PG8_LDA(dst, b, h) do { _Pragma("unroll") for (int m = 0; m < 4; ++m) _Pragma("unroll") for (int k = 0; k < 2; ++k) dst[m][k] = *(const PG8_LAS bf16x8*)(lds + PG8_SA(b, h) + aoff + m * 2048 + k * 1024); } while (0)
; #define PG8_LDB(dst, b, h) do { _Pragma("unroll") for (int n = 0; n < 2; ++n) _Pragma("unroll") for (int k = 0; k < 2; ++k) dst[n][k] = *(const PG8_LAS bf16x8*)(lds + PG8_SB(b, h) + boff + n * 2048 + k * 1024); } while (0)
; #define PG8_MMA(ai, bj, At, Bt) do { __builtin_amdgcn_s_setprio(1); _Pragma("unroll") for (int m = 0; m < 4; ++m) _Pragma("unroll") for (int n = 0; n < 2; ++n) _Pragma("unroll") for (int k = 0; k < 2; ++k) \
;         acc[ai][bj][m][n] = __builtin_amdgcn_mfma_f32_16x16x32_bf16(Bt[n][k], At[m][k], acc[ai][bj][m][n], 0, 0, 0); __builtin_amdgcn_s_setprio(0); } while (0)
; #define PG8_WAIT_V(n) asm volatile("s_waitcnt vmcnt(" #n ")" ::: "memory")
; #define PG8_WAIT_L(n) asm volatile("s_waitcnt lgkmcnt(" #n ")" ::: "memory")
; #define PG8_BAR __builtin_amdgcn_s_barrier()
; #define PG8_SCHED __builtin_amdgcn_sched_barrier(0)
; template <class Epi, class Sched, bool ALIGN_EPI = false, bool SP2 = false>
; __device__ __forceinline__ void gemm_phase(PG8_LAS unsigned char* lds, const Gemm g, const Sched& S, const Epi& E) {
;     ...
;             PG8_LDB(B0, 0, 0); PG8_LDB(B1, 0, 1); PG8_SCHED; PG8_LDA(At, 0, 0); PG8_STAGE(PG8_SA(1, 1), a1 + hstep, voffA);
;             PG8_WAIT_V(8); PG8_WAIT_L(0); PG8_BAR; PG8_MMA(0, 0, At, B0); PG8_MMA(0, 1, At, B1); PG8_BAR; PG8_SCHED;
;             PG8_LDA(At, 0, 1); PG8_STAGE(PG8_SB(0, 0), b2, voffB); PG8_STAGE(PG8_SB(0, 1), b2 + hstep, voffB); PG8_STAGE(PG8_SA(0, 0), a2, voffA);
;             PG8_WAIT_V(8); PG8_WAIT_L(0); PG8_BAR; PG8_MMA(1, 0, At, B0); PG8_MMA(1, 1, At, B1); PG8_BAR; PG8_SCHED;
.LBB0_1423:
	ds_read_b128 v[56:59], v173
	ds_read_b128 v[60:63], v173 offset:1024
	ds_read_b128 v[72:75], v173 offset:2048
	ds_read_b128 v[76:79], v173 offset:3072
	ds_read_b128 v[162:165], v174
	ds_read_b128 v[166:169], v174 offset:1024
	ds_read_b128 v[178:181], v174 offset:2048
	ds_read_b128 v[182:185], v174 offset:3072
	s_add_u32 s36, s34, 0xfffc0080
	s_addc_u32 s37, s35, -1
	s_cmp_eq_u32 s75, 12
	s_cselect_b32 s39, s25, s37
	s_cselect_b32 s38, s31, s36
	s_cselect_b32 s37, s23, s74
	s_cselect_b32 s36, s72, s73
	v_lshl_add_u64 v[218:219], s[34:35], 0, v[154:155]
	s_add_i32 m0, s42, 0xc000
	ds_read_b128 v[186:189], v175
	ds_read_b128 v[190:193], v175 offset:1024
	ds_read_b128 v[194:197], v175 offset:2048
	ds_read_b128 v[198:201], v175 offset:3072
	ds_read_b128 v[202:205], v175 offset:4096
	ds_read_b128 v[206:209], v175 offset:5120
	ds_read_b128 v[210:213], v175 offset:6144
	ds_read_b128 v[214:217], v175 offset:7168
	global_load_lds_dwordx4 v[218:219], off
	v_lshl_add_u64 v[218:219], s[34:35], 0, v[156:157]
	s_add_i32 m0, s42, 0xe000
	s_nop 0
	global_load_lds_dwordx4 v[218:219], off
	s_waitcnt vmcnt(8)
	s_waitcnt lgkmcnt(0)
	s_barrier
	s_setprio 1
	s_waitcnt lgkmcnt(0)
	v_mfma_f32_16x16x32_bf16 v[140:143], v[56:59], v[186:189], v[140:143]
	v_mfma_f32_16x16x32_bf16 v[136:139], v[72:75], v[186:189], v[136:139]
	v_mfma_f32_16x16x32_bf16 v[124:127], v[56:59], v[194:197], v[124:127]
	v_mfma_f32_16x16x32_bf16 v[120:123], v[72:75], v[194:197], v[120:123]
	v_mfma_f32_16x16x32_bf16 v[108:111], v[56:59], v[202:205], v[108:111]
	v_mfma_f32_16x16x32_bf16 v[104:107], v[72:75], v[202:205], v[104:107]
	v_mfma_f32_16x16x32_bf16 v[92:95], v[56:59], v[210:213], v[92:95]
	v_mfma_f32_16x16x32_bf16 v[88:91], v[72:75], v[210:213], v[88:91]
	v_mfma_f32_16x16x32_bf16 v[140:143], v[60:63], v[190:193], v[140:143]
	v_mfma_f32_16x16x32_bf16 v[136:139], v[76:79], v[190:193], v[136:139]
	v_mfma_f32_16x16x32_bf16 v[124:127], v[60:63], v[198:201], v[124:127]
	v_mfma_f32_16x16x32_bf16 v[120:123], v[76:79], v[198:201], v[120:123]
	v_mfma_f32_16x16x32_bf16 v[108:111], v[60:63], v[206:209], v[108:111]
	v_mfma_f32_16x16x32_bf16 v[104:107], v[76:79], v[206:209], v[104:107]
	v_mfma_f32_16x16x32_bf16 v[92:95], v[60:63], v[214:217], v[92:95]
	v_mfma_f32_16x16x32_bf16 v[88:91], v[76:79], v[214:217], v[88:91]
	s_setprio 0
	s_setprio 1
	v_mfma_f32_16x16x32_bf16 v[132:135], v[162:165], v[186:189], v[132:135]
	v_mfma_f32_16x16x32_bf16 v[128:131], v[178:181], v[186:189], v[128:131]
	v_mfma_f32_16x16x32_bf16 v[116:119], v[162:165], v[194:197], v[116:119]
	v_mfma_f32_16x16x32_bf16 v[112:115], v[178:181], v[194:197], v[112:115]
	v_mfma_f32_16x16x32_bf16 v[100:103], v[162:165], v[202:205], v[100:103]
	v_mfma_f32_16x16x32_bf16 v[96:99], v[178:181], v[202:205], v[96:99]
	v_mfma_f32_16x16x32_bf16 v[84:87], v[162:165], v[210:213], v[84:87]
	v_mfma_f32_16x16x32_bf16 v[80:83], v[178:181], v[210:213], v[80:83]
	v_mfma_f32_16x16x32_bf16 v[132:135], v[166:169], v[190:193], v[132:135]
	v_mfma_f32_16x16x32_bf16 v[128:131], v[182:185], v[190:193], v[128:131]
	v_mfma_f32_16x16x32_bf16 v[116:119], v[166:169], v[198:201], v[116:119]
	v_mfma_f32_16x16x32_bf16 v[112:115], v[182:185], v[198:201], v[112:115]
	v_mfma_f32_16x16x32_bf16 v[100:103], v[166:169], v[206:209], v[100:103]
	v_mfma_f32_16x16x32_bf16 v[96:99], v[182:185], v[206:209], v[96:99]
	v_mfma_f32_16x16x32_bf16 v[84:87], v[166:169], v[214:217], v[84:87]
	v_mfma_f32_16x16x32_bf16 v[80:83], v[182:185], v[214:217], v[80:83]
	s_setprio 0
	s_barrier
	s_add_i32 s76, s64, s41
	v_lshl_add_u64 v[218:219], s[36:37], 0, v[146:147]
	s_mov_b32 m0, s76
	ds_read_b128 v[186:189], v175 offset:16384
	ds_read_b128 v[190:193], v175 offset:17408
	ds_read_b128 v[194:197], v175 offset:18432
	ds_read_b128 v[198:201], v175 offset:19456
	ds_read_b128 v[202:205], v175 offset:20480
	ds_read_b128 v[206:209], v175 offset:21504
	ds_read_b128 v[210:213], v175 offset:22528
	ds_read_b128 v[214:217], v175 offset:23552
	global_load_lds_dwordx4 v[218:219], off
	s_add_i32 m0, s76, 0x2000
	s_add_u32 s76, s36, 0x40000
	v_lshl_add_u64 v[220:221], s[36:37], 0, v[150:151]
	s_addc_u32 s77, s37, 0
	s_add_i32 s80, s65, s41
	global_load_lds_dwordx4 v[220:221], off
	v_lshl_add_u64 v[222:223], s[76:77], 0, v[146:147]
	s_mov_b32 m0, s80
	v_lshl_add_u64 v[224:225], s[38:39], 0, v[148:149]
	global_load_lds_dwordx4 v[222:223], off
	v_lshl_add_u64 v[222:223], s[76:77], 0, v[150:151]
	s_add_i32 m0, s80, 0x2000
	s_nop 0
	global_load_lds_dwordx4 v[222:223], off
	s_waitcnt vmcnt(6)
	s_waitcnt lgkmcnt(0)
	s_barrier
; #define PG8_STAGE(bufoff, gbase, voff) do { _Pragma("unroll") for (int _i = 0; _i < 2; ++_i) \
;         __builtin_amdgcn_global_load_lds((const unsigned*)((const char*)(gbase) + (voff)[_i]), (PG8_LAS unsigned*)(lds + (bufoff) + ldsw + _i * 8192), 16, 0, 0); } while (0)
; #define PG8_LDA(dst, b, h) do { _Pragma("unroll") for (int m = 0; m < 4; ++m) _Pragma("unroll") for (int k = 0; k < 2; ++k) dst[m][k] = *(const PG8_LAS bf16x8*)(lds + PG8_SA(b, h) + aoff + m * 2048 + k * 1024); } while (0)
; #define PG8_LDB(dst, b, h) do { _Pragma("unroll") for (int n = 0; n < 2; ++n) _Pragma("unroll") for (int k = 0; k < 2; ++k) dst[n][k] = *(const PG8_LAS bf16x8*)(lds + PG8_SB(b, h) + boff + n * 2048 + k * 1024); } while (0)
; #define PG8_MMA(ai, bj, At, Bt) do { __builtin_amdgcn_s_setprio(1); _Pragma("unroll") for (int m = 0; m < 4; ++m) _Pragma("unroll") for (int n = 0; n < 2; ++n) _Pragma("unroll") for (int k = 0; k < 2; ++k) \
;         acc[ai][bj][m][n] = __builtin_amdgcn_mfma_f32_16x16x32_bf16(Bt[n][k], At[m][k], acc[ai][bj][m][n], 0, 0, 0); __builtin_amdgcn_s_setprio(0); } while (0)
; #define PG8_WAIT_V(n) asm volatile("s_waitcnt vmcnt(" #n ")" ::: "memory")
; #define PG8_WAIT_L(n) asm volatile("s_waitcnt lgkmcnt(" #n ")" ::: "memory")
; #define PG8_BAR __builtin_amdgcn_s_barrier()
; #define PG8_SCHED __builtin_amdgcn_sched_barrier(0)
; template <class Epi, class Sched, bool ALIGN_EPI = false, bool SP2 = false>
; __device__ __forceinline__ void gemm_phase(PG8_LAS unsigned char* lds, const Gemm g, const Sched& S, const Epi& E) {
;     ...
;             PG8_WAIT_V(8); PG8_WAIT_L(0); PG8_BAR; PG8_MMA(1, 0, At, B0); PG8_MMA(1, 1, At, B1); PG8_BAR; PG8_SCHED;
;             PG8_LDB(B0, 1, 0); PG8_LDB(B1, 1, 1); PG8_SCHED; PG8_LDA(At, 1, 0); PG8_STAGE(PG8_SA(0, 1), a2 + hstep, voffA);
;             PG8_WAIT_V(8); PG8_WAIT_L(0); PG8_BAR; PG8_MMA(0, 0, At, B0); PG8_MMA(0, 1, At, B1); PG8_BAR; PG8_SCHED;
	s_setprio 1
	s_waitcnt lgkmcnt(0)
	v_mfma_f32_16x16x32_bf16 v[68:71], v[56:59], v[186:189], v[68:71]
	v_mfma_f32_16x16x32_bf16 v[64:67], v[72:75], v[186:189], v[64:67]
	v_mfma_f32_16x16x32_bf16 v[44:47], v[56:59], v[194:197], v[44:47]
	v_mfma_f32_16x16x32_bf16 v[40:43], v[72:75], v[194:197], v[40:43]
	v_mfma_f32_16x16x32_bf16 v[28:31], v[56:59], v[202:205], v[28:31]
	v_mfma_f32_16x16x32_bf16 v[24:27], v[72:75], v[202:205], v[24:27]
	v_mfma_f32_16x16x32_bf16 v[12:15], v[56:59], v[210:213], v[12:15]
	v_mfma_f32_16x16x32_bf16 v[8:11], v[72:75], v[210:213], v[8:11]
	v_mfma_f32_16x16x32_bf16 v[68:71], v[60:63], v[190:193], v[68:71]
	v_mfma_f32_16x16x32_bf16 v[64:67], v[76:79], v[190:193], v[64:67]
	v_mfma_f32_16x16x32_bf16 v[44:47], v[60:63], v[198:201], v[44:47]
	v_mfma_f32_16x16x32_bf16 v[40:43], v[76:79], v[198:201], v[40:43]
	v_mfma_f32_16x16x32_bf16 v[28:31], v[60:63], v[206:209], v[28:31]
	v_mfma_f32_16x16x32_bf16 v[24:27], v[76:79], v[206:209], v[24:27]
	v_mfma_f32_16x16x32_bf16 v[12:15], v[60:63], v[214:217], v[12:15]
	v_mfma_f32_16x16x32_bf16 v[8:11], v[76:79], v[214:217], v[8:11]
	s_setprio 0
	v_lshl_add_u64 v[222:223], s[38:39], 0, v[144:145]
	s_mov_b32 m0, s42
	s_nop 0
	global_load_lds_dwordx4 v[222:223], off
	s_mov_b32 m0, s43
	s_nop 0
	global_load_lds_dwordx4 v[224:225], off
	s_setprio 1
	v_mfma_f32_16x16x32_bf16 v[52:55], v[162:165], v[186:189], v[52:55]
	v_mfma_f32_16x16x32_bf16 v[48:51], v[178:181], v[186:189], v[48:51]
	v_mfma_f32_16x16x32_bf16 v[36:39], v[162:165], v[194:197], v[36:39]
	v_mfma_f32_16x16x32_bf16 v[32:35], v[178:181], v[194:197], v[32:35]
	v_mfma_f32_16x16x32_bf16 v[20:23], v[162:165], v[202:205], v[20:23]
	v_mfma_f32_16x16x32_bf16 v[16:19], v[178:181], v[202:205], v[16:19]
	v_mfma_f32_16x16x32_bf16 v[4:7], v[162:165], v[210:213], v[4:7]
	v_mfma_f32_16x16x32_bf16 v[0:3], v[178:181], v[210:213], v[0:3]
	v_mfma_f32_16x16x32_bf16 v[52:55], v[166:169], v[190:193], v[52:55]
	v_mfma_f32_16x16x32_bf16 v[48:51], v[182:185], v[190:193], v[48:51]
	v_mfma_f32_16x16x32_bf16 v[36:39], v[166:169], v[198:201], v[36:39]
	v_mfma_f32_16x16x32_bf16 v[32:35], v[182:185], v[198:201], v[32:35]
	v_mfma_f32_16x16x32_bf16 v[20:23], v[166:169], v[206:209], v[20:23]
	v_mfma_f32_16x16x32_bf16 v[16:19], v[182:185], v[206:209], v[16:19]
	v_mfma_f32_16x16x32_bf16 v[4:7], v[166:169], v[214:217], v[4:7]
	v_mfma_f32_16x16x32_bf16 v[0:3], v[182:185], v[214:217], v[0:3]
	s_setprio 0
	s_barrier
	s_add_i32 s76, 0, 0x18000
	s_add_i32 s77, 0, 0x1c000
	v_add_u32_e32 v76, s76, v171
	v_add_u32_e32 v152, s77, v171
	ds_read_b128 v[56:59], v76
	ds_read_b128 v[60:63], v76 offset:1024
	ds_read_b128 v[72:75], v76 offset:2048
	ds_read_b128 v[76:79], v76 offset:3072
	ds_read_b128 v[162:165], v152
	ds_read_b128 v[166:169], v152 offset:1024
	ds_read_b128 v[178:181], v152 offset:2048
	ds_read_b128 v[182:185], v152 offset:3072
	s_add_u32 s38, s38, 0x40000
	s_addc_u32 s39, s39, 0
	s_mov_b32 m0, s46
	v_lshl_add_u64 v[228:229], s[38:39], 0, v[144:145]
	ds_read_b128 v[186:189], v175 offset:32768
	ds_read_b128 v[190:193], v175 offset:33792
	ds_read_b128 v[194:197], v175 offset:34816
	ds_read_b128 v[198:201], v175 offset:35840
	ds_read_b128 v[202:205], v175 offset:36864
	ds_read_b128 v[206:209], v175 offset:37888
	ds_read_b128 v[210:213], v175 offset:38912
	ds_read_b128 v[214:217], v175 offset:39936
	global_load_lds_dwordx4 v[228:229], off
	v_lshl_add_u64 v[228:229], s[38:39], 0, v[148:149]
	s_mov_b32 m0, s47
	s_nop 0
	global_load_lds_dwordx4 v[228:229], off
	s_waitcnt vmcnt(8)
	s_waitcnt lgkmcnt(0)
	s_barrier
	s_setprio 1
	s_waitcnt lgkmcnt(0)
	v_mfma_f32_16x16x32_bf16 v[140:143], v[56:59], v[186:189], v[140:143]
	v_mfma_f32_16x16x32_bf16 v[136:139], v[72:75], v[186:189], v[136:139]
	v_mfma_f32_16x16x32_bf16 v[124:127], v[56:59], v[194:197], v[124:127]
	v_mfma_f32_16x16x32_bf16 v[120:123], v[72:75], v[194:197], v[120:123]
	v_mfma_f32_16x16x32_bf16 v[108:111], v[56:59], v[202:205], v[108:111]
	v_mfma_f32_16x16x32_bf16 v[104:107], v[72:75], v[202:205], v[104:107]
	v_mfma_f32_16x16x32_bf16 v[92:95], v[56:59], v[210:213], v[92:95]
	v_mfma_f32_16x16x32_bf16 v[88:91], v[72:75], v[210:213], v[88:91]
	v_mfma_f32_16x16x32_bf16 v[140:143], v[60:63], v[190:193], v[140:143]
	v_mfma_f32_16x16x32_bf16 v[136:139], v[76:79], v[190:193], v[136:139]
	v_mfma_f32_16x16x32_bf16 v[124:127], v[60:63], v[198:201], v[124:127]
	v_mfma_f32_16x16x32_bf16 v[120:123], v[76:79], v[198:201], v[120:123]
	v_mfma_f32_16x16x32_bf16 v[108:111], v[60:63], v[206:209], v[108:111]
	v_mfma_f32_16x16x32_bf16 v[104:107], v[76:79], v[206:209], v[104:107]
	v_mfma_f32_16x16x32_bf16 v[92:95], v[60:63], v[214:217], v[92:95]
	v_mfma_f32_16x16x32_bf16 v[88:91], v[76:79], v[214:217], v[88:91]
	s_setprio 0
	s_setprio 1
	v_mfma_f32_16x16x32_bf16 v[132:135], v[162:165], v[186:189], v[132:135]
	v_mfma_f32_16x16x32_bf16 v[128:131], v[178:181], v[186:189], v[128:131]
	v_mfma_f32_16x16x32_bf16 v[116:119], v[162:165], v[194:197], v[116:119]
	v_mfma_f32_16x16x32_bf16 v[112:115], v[178:181], v[194:197], v[112:115]
	v_mfma_f32_16x16x32_bf16 v[100:103], v[162:165], v[202:205], v[100:103]
	v_mfma_f32_16x16x32_bf16 v[96:99], v[178:181], v[202:205], v[96:99]
	v_mfma_f32_16x16x32_bf16 v[84:87], v[162:165], v[210:213], v[84:87]
	v_mfma_f32_16x16x32_bf16 v[80:83], v[178:181], v[210:213], v[80:83]
	v_mfma_f32_16x16x32_bf16 v[132:135], v[166:169], v[190:193], v[132:135]
	v_mfma_f32_16x16x32_bf16 v[128:131], v[182:185], v[190:193], v[128:131]
	v_mfma_f32_16x16x32_bf16 v[116:119], v[166:169], v[198:201], v[116:119]
	v_mfma_f32_16x16x32_bf16 v[112:115], v[182:185], v[198:201], v[112:115]
	v_mfma_f32_16x16x32_bf16 v[100:103], v[166:169], v[206:209], v[100:103]
	v_mfma_f32_16x16x32_bf16 v[96:99], v[182:185], v[206:209], v[96:99]
	v_mfma_f32_16x16x32_bf16 v[84:87], v[166:169], v[214:217], v[84:87]
	v_mfma_f32_16x16x32_bf16 v[80:83], v[182:185], v[214:217], v[80:83]
	s_setprio 0
	s_barrier
; #define PG8_STAGE(bufoff, gbase, voff) do { _Pragma("unroll") for (int _i = 0; _i < 2; ++_i) \
;         __builtin_amdgcn_global_load_lds((const unsigned*)((const char*)(gbase) + (voff)[_i]), (PG8_LAS unsigned*)(lds + (bufoff) + ldsw + _i * 8192), 16, 0, 0); } while (0)
; #define PG8_LDA(dst, b, h) do { _Pragma("unroll") for (int m = 0; m < 4; ++m) _Pragma("unroll") for (int k = 0; k < 2; ++k) dst[m][k] = *(const PG8_LAS bf16x8*)(lds + PG8_SA(b, h) + aoff + m * 2048 + k * 1024); } while (0)
; #define PG8_MMA(ai, bj, At, Bt) do { __builtin_amdgcn_s_setprio(1); _Pragma("unroll") for (int m = 0; m < 4; ++m) _Pragma("unroll") for (int n = 0; n < 2; ++n) _Pragma("unroll") for (int k = 0; k < 2; ++k) \
;         acc[ai][bj][m][n] = __builtin_amdgcn_mfma_f32_16x16x32_bf16(Bt[n][k], At[m][k], acc[ai][bj][m][n], 0, 0, 0); __builtin_amdgcn_s_setprio(0); } while (0)
; #define PG8_WAIT_V(n) asm volatile("s_waitcnt vmcnt(" #n ")" ::: "memory")
; #define PG8_WAIT_L(n) asm volatile("s_waitcnt lgkmcnt(" #n ")" ::: "memory")
; #define PG8_BAR __builtin_amdgcn_s_barrier()
; #define PG8_SCHED __builtin_amdgcn_sched_barrier(0)
; template <class Epi, class Sched, bool ALIGN_EPI = false, bool SP2 = false>
; __device__ __forceinline__ void gemm_phase(PG8_LAS unsigned char* lds, const Gemm g, const Sched& S, const Epi& E) {
;     ...
;             PG8_LDA(At, 1, 1); PG8_STAGE(PG8_SB(1, 0), b3, voffB); PG8_STAGE(PG8_SB(1, 1), b3 + hstep, voffB); PG8_STAGE(PG8_SA(1, 0), a3, voffA);
;             PG8_WAIT_V(8); PG8_WAIT_L(0); PG8_BAR; PG8_MMA(1, 0, At, B0); PG8_MMA(1, 1, At, B1); PG8_BAR; PG8_SCHED;
	s_add_i32 s38, s76, s41
	v_lshl_add_u64 v[218:219], v[218:219], 0, s[18:19]
	s_mov_b32 m0, s38
	ds_read_b128 v[186:189], v175 offset:49152
	ds_read_b128 v[190:193], v175 offset:50176
	ds_read_b128 v[194:197], v175 offset:51200
	ds_read_b128 v[198:201], v175 offset:52224
	ds_read_b128 v[202:205], v175 offset:53248
	ds_read_b128 v[206:209], v175 offset:54272
	ds_read_b128 v[210:213], v175 offset:55296
	ds_read_b128 v[214:217], v175 offset:56320
	global_load_lds_dwordx4 v[218:219], off
	s_add_i32 m0, s38, 0x2000
	s_add_u32 s36, s36, 0x40080
	v_lshl_add_u64 v[218:219], v[220:221], 0, s[18:19]
	s_addc_u32 s37, s37, 0
	s_add_i32 s38, s77, s41
	global_load_lds_dwordx4 v[218:219], off
	v_lshl_add_u64 v[218:219], s[36:37], 0, v[146:147]
	s_mov_b32 m0, s38
	s_nop 0
	global_load_lds_dwordx4 v[218:219], off
	v_lshl_add_u64 v[218:219], s[36:37], 0, v[150:151]
	s_add_i32 m0, s38, 0x2000
	s_nop 0
	global_load_lds_dwordx4 v[218:219], off
	s_waitcnt vmcnt(6)
	s_waitcnt lgkmcnt(0)
	s_barrier
	s_setprio 1
	s_waitcnt lgkmcnt(0)
	v_mfma_f32_16x16x32_bf16 v[68:71], v[56:59], v[186:189], v[68:71]
	v_mfma_f32_16x16x32_bf16 v[64:67], v[72:75], v[186:189], v[64:67]
	v_mfma_f32_16x16x32_bf16 v[44:47], v[56:59], v[194:197], v[44:47]
	v_mfma_f32_16x16x32_bf16 v[40:43], v[72:75], v[194:197], v[40:43]
	v_mfma_f32_16x16x32_bf16 v[28:31], v[56:59], v[202:205], v[28:31]
	v_mfma_f32_16x16x32_bf16 v[24:27], v[72:75], v[202:205], v[24:27]
	v_mfma_f32_16x16x32_bf16 v[12:15], v[56:59], v[210:213], v[12:15]
	v_mfma_f32_16x16x32_bf16 v[8:11], v[72:75], v[210:213], v[8:11]
	v_mfma_f32_16x16x32_bf16 v[68:71], v[60:63], v[190:193], v[68:71]
	v_mfma_f32_16x16x32_bf16 v[64:67], v[76:79], v[190:193], v[64:67]
	v_mfma_f32_16x16x32_bf16 v[44:47], v[60:63], v[198:201], v[44:47]
	v_mfma_f32_16x16x32_bf16 v[40:43], v[76:79], v[198:201], v[40:43]
	v_mfma_f32_16x16x32_bf16 v[28:31], v[60:63], v[206:209], v[28:31]
	v_mfma_f32_16x16x32_bf16 v[24:27], v[76:79], v[206:209], v[24:27]
	v_mfma_f32_16x16x32_bf16 v[12:15], v[60:63], v[214:217], v[12:15]
	v_mfma_f32_16x16x32_bf16 v[8:11], v[76:79], v[214:217], v[8:11]
	s_setprio 0
	v_lshl_add_u64 v[218:219], v[222:223], 0, s[18:19]
	s_mov_b32 m0, s53
	s_nop 0
	global_load_lds_dwordx4 v[218:219], off
	v_lshl_add_u64 v[218:219], v[224:225], 0, s[18:19]
	s_mov_b32 m0, s60
	s_nop 0
	global_load_lds_dwordx4 v[218:219], off
	s_setprio 1
	v_mfma_f32_16x16x32_bf16 v[52:55], v[162:165], v[186:189], v[52:55]
	v_mfma_f32_16x16x32_bf16 v[48:51], v[178:181], v[186:189], v[48:51]
	v_mfma_f32_16x16x32_bf16 v[36:39], v[162:165], v[194:197], v[36:39]
	v_mfma_f32_16x16x32_bf16 v[32:35], v[178:181], v[194:197], v[32:35]
	v_mfma_f32_16x16x32_bf16 v[20:23], v[162:165], v[202:205], v[20:23]
	v_mfma_f32_16x16x32_bf16 v[16:19], v[178:181], v[202:205], v[16:19]
	v_mfma_f32_16x16x32_bf16 v[4:7], v[162:165], v[210:213], v[4:7]
	v_mfma_f32_16x16x32_bf16 v[0:3], v[178:181], v[210:213], v[0:3]
	v_mfma_f32_16x16x32_bf16 v[52:55], v[166:169], v[190:193], v[52:55]
	v_mfma_f32_16x16x32_bf16 v[48:51], v[182:185], v[190:193], v[48:51]
	v_mfma_f32_16x16x32_bf16 v[36:39], v[166:169], v[198:201], v[36:39]
	v_mfma_f32_16x16x32_bf16 v[32:35], v[182:185], v[198:201], v[32:35]
	v_mfma_f32_16x16x32_bf16 v[20:23], v[166:169], v[206:209], v[20:23]
	v_mfma_f32_16x16x32_bf16 v[16:19], v[182:185], v[206:209], v[16:19]
	v_mfma_f32_16x16x32_bf16 v[4:7], v[166:169], v[214:217], v[4:7]
	v_mfma_f32_16x16x32_bf16 v[0:3], v[182:185], v[214:217], v[0:3]
	s_setprio 0
	s_barrier
	s_add_i32 s75, s75, 2
	s_add_u32 s34, s34, 0x100
	s_addc_u32 s35, s35, 0
	s_add_u32 s73, s73, 0x100
	s_addc_u32 s74, s74, 0
	s_cmp_gt_u32 s75, 13
	s_cbranch_scc0 .LBB0_1423
	s_and_b64 vcc, exec, s[20:21]
	s_cbranch_vccz .LBB0_1426
	s_barrier

; #define PG8_STAGE(bufoff, gbase, voff) do { _Pragma("unroll") for (int _i = 0; _i < 2; ++_i) \
;         __builtin_amdgcn_global_load_lds((const unsigned*)((const char*)(gbase) + (voff)[_i]), (PG8_LAS unsigned*)(lds + (bufoff) + ldsw + _i * 8192), 16, 0, 0); } while (0)
; #define PG8_LDA(dst, b, h) do { _Pragma("unroll") for (int m = 0; m < 4; ++m) _Pragma("unroll") for (int k = 0; k < 2; ++k) dst[m][k] = *(const PG8_LAS bf16x8*)(lds + PG8_SA(b, h) + aoff + m * 2048 + k * 1024); } while (0)
; #define PG8_LDB(dst, b, h) do { _Pragma("unroll") for (int n = 0; n < 2; ++n) _Pragma("unroll") for (int k = 0; k < 2; ++k) dst[n][k] = *(const PG8_LAS bf16x8*)(lds + PG8_SB(b, h) + boff + n * 2048 + k * 1024); } while (0)
; #define PG8_MMA(ai, bj, At, Bt) do { __builtin_amdgcn_s_setprio(1); _Pragma("unroll") for (int m = 0; m < 4; ++m) _Pragma("unroll") for (int n = 0; n < 2; ++n) _Pragma("unroll") for (int k = 0; k < 2; ++k) \
;         acc[ai][bj][m][n] = __builtin_amdgcn_mfma_f32_16x16x32_bf16(Bt[n][k], At[m][k], acc[ai][bj][m][n], 0, 0, 0); __builtin_amdgcn_s_setprio(0); } while (0)
; #define PG8_WAIT_V(n) asm volatile("s_waitcnt vmcnt(" #n ")" ::: "memory")
; #define PG8_WAIT_L(n) asm volatile("s_waitcnt lgkmcnt(" #n ")" ::: "memory")
; #define PG8_BAR __builtin_amdgcn_s_barrier()
; #define PG8_SCHED __builtin_amdgcn_sched_barrier(0)
; template <class Epi, class Sched, bool ALIGN_EPI = false, bool SP2 = false>
; __device__ __forceinline__ void gemm_phase(PG8_LAS unsigned char* lds, const Gemm g, const Sched& S, const Epi& E) {
;     ...
;             PG8_LDB(B0, 0, 0); PG8_LDB(B1, 0, 1); PG8_SCHED; PG8_LDA(At, 0, 0); PG8_STAGE(PG8_SA(1, 1), a1 + hstep, voffA);
;             PG8_WAIT_V(8); PG8_WAIT_L(0); PG8_BAR; PG8_MMA(0, 0, At, B0); PG8_MMA(0, 1, At, B1); PG8_BAR; PG8_SCHED;
;             PG8_LDA(At, 0, 1); PG8_STAGE(PG8_SB(0, 0), b2, voffB); PG8_STAGE(PG8_SB(0, 1), b2 + hstep, voffB); PG8_STAGE(PG8_SA(0, 0), a2, voffA);
;             PG8_WAIT_V(8); PG8_WAIT_L(0); PG8_BAR; PG8_MMA(1, 0, At, B0); PG8_MMA(1, 1, At, B1); PG8_BAR; PG8_SCHED;
.LBB0_1540:
	ds_read_b128 v[144:147], v151
	ds_read_b128 v[156:159], v151 offset:1024
	ds_read_b128 v[160:163], v151 offset:2048
	ds_read_b128 v[164:167], v151 offset:3072
	ds_read_b128 v[168:171], v152
	ds_read_b128 v[172:175], v152 offset:1024
	ds_read_b128 v[176:179], v152 offset:2048
	ds_read_b128 v[180:183], v152 offset:3072
	s_add_u32 s34, s30, 0xfffc0080
	s_addc_u32 s35, s31, -1
	s_cmp_eq_u32 s65, 12
	s_cselect_b32 s37, s23, s35
	s_cselect_b32 s36, s61, s34
	s_cselect_b32 s35, s19, s64
	s_cselect_b32 s34, s62, s63
	v_lshl_add_u64 v[216:217], s[30:31], 0, v[136:137]
	s_add_i32 m0, s29, 0xc000
	ds_read_b128 v[184:187], v153
	ds_read_b128 v[188:191], v153 offset:1024
	ds_read_b128 v[192:195], v153 offset:2048
	ds_read_b128 v[196:199], v153 offset:3072
	ds_read_b128 v[200:203], v153 offset:4096
	ds_read_b128 v[204:207], v153 offset:5120
	ds_read_b128 v[208:211], v153 offset:6144
	ds_read_b128 v[212:215], v153 offset:7168
	global_load_lds_dwordx4 v[216:217], off
	v_lshl_add_u64 v[216:217], s[30:31], 0, v[138:139]
	s_add_i32 m0, s29, 0xe000
	s_nop 0
	global_load_lds_dwordx4 v[216:217], off
	s_waitcnt vmcnt(8)
	s_waitcnt lgkmcnt(0)
	s_barrier
	s_setprio 1
	s_waitcnt lgkmcnt(0)
	v_mfma_f32_16x16x32_bf16 v[124:127], v[144:147], v[184:187], v[124:127]
	v_mfma_f32_16x16x32_bf16 v[120:123], v[160:163], v[184:187], v[120:123]
	v_mfma_f32_16x16x32_bf16 v[108:111], v[144:147], v[192:195], v[108:111]
	v_mfma_f32_16x16x32_bf16 v[104:107], v[160:163], v[192:195], v[104:107]
	v_mfma_f32_16x16x32_bf16 v[92:95], v[144:147], v[200:203], v[92:95]
	v_mfma_f32_16x16x32_bf16 v[88:91], v[160:163], v[200:203], v[88:91]
	v_mfma_f32_16x16x32_bf16 v[76:79], v[144:147], v[208:211], v[76:79]
	v_mfma_f32_16x16x32_bf16 v[72:75], v[160:163], v[208:211], v[72:75]
	v_mfma_f32_16x16x32_bf16 v[124:127], v[156:159], v[188:191], v[124:127]
	v_mfma_f32_16x16x32_bf16 v[120:123], v[164:167], v[188:191], v[120:123]
	v_mfma_f32_16x16x32_bf16 v[108:111], v[156:159], v[196:199], v[108:111]
	v_mfma_f32_16x16x32_bf16 v[104:107], v[164:167], v[196:199], v[104:107]
	v_mfma_f32_16x16x32_bf16 v[92:95], v[156:159], v[204:207], v[92:95]
	v_mfma_f32_16x16x32_bf16 v[88:91], v[164:167], v[204:207], v[88:91]
	v_mfma_f32_16x16x32_bf16 v[76:79], v[156:159], v[212:215], v[76:79]
	v_mfma_f32_16x16x32_bf16 v[72:75], v[164:167], v[212:215], v[72:75]
	s_setprio 0
	s_setprio 1
	v_mfma_f32_16x16x32_bf16 v[116:119], v[168:171], v[184:187], v[116:119]
	v_mfma_f32_16x16x32_bf16 v[112:115], v[176:179], v[184:187], v[112:115]
	v_mfma_f32_16x16x32_bf16 v[100:103], v[168:171], v[192:195], v[100:103]
	v_mfma_f32_16x16x32_bf16 v[96:99], v[176:179], v[192:195], v[96:99]
	v_mfma_f32_16x16x32_bf16 v[84:87], v[168:171], v[200:203], v[84:87]
	v_mfma_f32_16x16x32_bf16 v[80:83], v[176:179], v[200:203], v[80:83]
	v_mfma_f32_16x16x32_bf16 v[68:71], v[168:171], v[208:211], v[68:71]
	v_mfma_f32_16x16x32_bf16 v[64:67], v[176:179], v[208:211], v[64:67]
	v_mfma_f32_16x16x32_bf16 v[116:119], v[172:175], v[188:191], v[116:119]
	v_mfma_f32_16x16x32_bf16 v[112:115], v[180:183], v[188:191], v[112:115]
	v_mfma_f32_16x16x32_bf16 v[100:103], v[172:175], v[196:199], v[100:103]
	v_mfma_f32_16x16x32_bf16 v[96:99], v[180:183], v[196:199], v[96:99]
	v_mfma_f32_16x16x32_bf16 v[84:87], v[172:175], v[204:207], v[84:87]
	v_mfma_f32_16x16x32_bf16 v[80:83], v[180:183], v[204:207], v[80:83]
	v_mfma_f32_16x16x32_bf16 v[68:71], v[172:175], v[212:215], v[68:71]
	v_mfma_f32_16x16x32_bf16 v[64:67], v[180:183], v[212:215], v[64:67]
	s_setprio 0
	s_barrier
	s_add_i32 s66, s52, s39
	v_lshl_add_u64 v[216:217], s[34:35], 0, v[132:133]
	s_mov_b32 m0, s66
	ds_read_b128 v[184:187], v153 offset:16384
	ds_read_b128 v[188:191], v153 offset:17408
	ds_read_b128 v[192:195], v153 offset:18432
	ds_read_b128 v[196:199], v153 offset:19456
	ds_read_b128 v[200:203], v153 offset:20480
	ds_read_b128 v[204:207], v153 offset:21504
	ds_read_b128 v[208:211], v153 offset:22528
	ds_read_b128 v[212:215], v153 offset:23552
	global_load_lds_dwordx4 v[216:217], off
	s_add_i32 m0, s66, 0x2000
	s_add_u32 s66, s34, 0x40000
	v_lshl_add_u64 v[218:219], s[34:35], 0, v[128:129]
	s_addc_u32 s67, s35, 0
	s_add_i32 s68, s53, s39
	global_load_lds_dwordx4 v[218:219], off
	v_lshl_add_u64 v[220:221], s[66:67], 0, v[132:133]
	s_mov_b32 m0, s68
	v_lshl_add_u64 v[222:223], s[36:37], 0, v[130:131]
	global_load_lds_dwordx4 v[220:221], off
	v_lshl_add_u64 v[220:221], s[66:67], 0, v[128:129]
	s_add_i32 m0, s68, 0x2000
	s_nop 0
	global_load_lds_dwordx4 v[220:221], off
	s_waitcnt vmcnt(6)
	s_waitcnt lgkmcnt(0)
	s_barrier
; #define PG8_STAGE(bufoff, gbase, voff) do { _Pragma("unroll") for (int _i = 0; _i < 2; ++_i) \
;         __builtin_amdgcn_global_load_lds((const unsigned*)((const char*)(gbase) + (voff)[_i]), (PG8_LAS unsigned*)(lds + (bufoff) + ldsw + _i * 8192), 16, 0, 0); } while (0)
; #define PG8_LDA(dst, b, h) do { _Pragma("unroll") for (int m = 0; m < 4; ++m) _Pragma("unroll") for (int k = 0; k < 2; ++k) dst[m][k] = *(const PG8_LAS bf16x8*)(lds + PG8_SA(b, h) + aoff + m * 2048 + k * 1024); } while (0)
; #define PG8_LDB(dst, b, h) do { _Pragma("unroll") for (int n = 0; n < 2; ++n) _Pragma("unroll") for (int k = 0; k < 2; ++k) dst[n][k] = *(const PG8_LAS bf16x8*)(lds + PG8_SB(b, h) + boff + n * 2048 + k * 1024); } while (0)
; #define PG8_MMA(ai, bj, At, Bt) do { __builtin_amdgcn_s_setprio(1); _Pragma("unroll") for (int m = 0; m < 4; ++m) _Pragma("unroll") for (int n = 0; n < 2; ++n) _Pragma("unroll") for (int k = 0; k < 2; ++k) \
;         acc[ai][bj][m][n] = __builtin_amdgcn_mfma_f32_16x16x32_bf16(Bt[n][k], At[m][k], acc[ai][bj][m][n], 0, 0, 0); __builtin_amdgcn_s_setprio(0); } while (0)
; #define PG8_WAIT_V(n) asm volatile("s_waitcnt vmcnt(" #n ")" ::: "memory")
; #define PG8_WAIT_L(n) asm volatile("s_waitcnt lgkmcnt(" #n ")" ::: "memory")
; #define PG8_BAR __builtin_amdgcn_s_barrier()
; #define PG8_SCHED __builtin_amdgcn_sched_barrier(0)
; template <class Epi, class Sched, bool ALIGN_EPI = false, bool SP2 = false>
; __device__ __forceinline__ void gemm_phase(PG8_LAS unsigned char* lds, const Gemm g, const Sched& S, const Epi& E) {
;     ...
;             PG8_WAIT_V(8); PG8_WAIT_L(0); PG8_BAR; PG8_MMA(1, 0, At, B0); PG8_MMA(1, 1, At, B1); PG8_BAR; PG8_SCHED;
;             PG8_LDB(B0, 1, 0); PG8_LDB(B1, 1, 1); PG8_SCHED; PG8_LDA(At, 1, 0); PG8_STAGE(PG8_SA(0, 1), a2 + hstep, voffA);
;             PG8_WAIT_V(8); PG8_WAIT_L(0); PG8_BAR; PG8_MMA(0, 0, At, B0); PG8_MMA(0, 1, At, B1); PG8_BAR; PG8_SCHED;
	s_setprio 1
	s_waitcnt lgkmcnt(0)
	v_mfma_f32_16x16x32_bf16 v[60:63], v[144:147], v[184:187], v[60:63]
	v_mfma_f32_16x16x32_bf16 v[56:59], v[160:163], v[184:187], v[56:59]
	v_mfma_f32_16x16x32_bf16 v[44:47], v[144:147], v[192:195], v[44:47]
	v_mfma_f32_16x16x32_bf16 v[40:43], v[160:163], v[192:195], v[40:43]
	v_mfma_f32_16x16x32_bf16 v[28:31], v[144:147], v[200:203], v[28:31]
	v_mfma_f32_16x16x32_bf16 v[24:27], v[160:163], v[200:203], v[24:27]
	v_mfma_f32_16x16x32_bf16 v[12:15], v[144:147], v[208:211], v[12:15]
	v_mfma_f32_16x16x32_bf16 v[8:11], v[160:163], v[208:211], v[8:11]
	v_mfma_f32_16x16x32_bf16 v[60:63], v[156:159], v[188:191], v[60:63]
	v_mfma_f32_16x16x32_bf16 v[56:59], v[164:167], v[188:191], v[56:59]
	v_mfma_f32_16x16x32_bf16 v[44:47], v[156:159], v[196:199], v[44:47]
	v_mfma_f32_16x16x32_bf16 v[40:43], v[164:167], v[196:199], v[40:43]
	v_mfma_f32_16x16x32_bf16 v[28:31], v[156:159], v[204:207], v[28:31]
	v_mfma_f32_16x16x32_bf16 v[24:27], v[164:167], v[204:207], v[24:27]
	v_mfma_f32_16x16x32_bf16 v[12:15], v[156:159], v[212:215], v[12:15]
	v_mfma_f32_16x16x32_bf16 v[8:11], v[164:167], v[212:215], v[8:11]
	s_setprio 0
	v_lshl_add_u64 v[220:221], s[36:37], 0, v[134:135]
	s_mov_b32 m0, s29
	s_nop 0
	global_load_lds_dwordx4 v[220:221], off
	s_mov_b32 m0, s42
	s_nop 0
	global_load_lds_dwordx4 v[222:223], off
	s_setprio 1
	v_mfma_f32_16x16x32_bf16 v[52:55], v[168:171], v[184:187], v[52:55]
	v_mfma_f32_16x16x32_bf16 v[48:51], v[176:179], v[184:187], v[48:51]
	v_mfma_f32_16x16x32_bf16 v[36:39], v[168:171], v[192:195], v[36:39]
	v_mfma_f32_16x16x32_bf16 v[32:35], v[176:179], v[192:195], v[32:35]
	v_mfma_f32_16x16x32_bf16 v[20:23], v[168:171], v[200:203], v[20:23]
	v_mfma_f32_16x16x32_bf16 v[16:19], v[176:179], v[200:203], v[16:19]
	v_mfma_f32_16x16x32_bf16 v[4:7], v[168:171], v[208:211], v[4:7]
	v_mfma_f32_16x16x32_bf16 v[0:3], v[176:179], v[208:211], v[0:3]
	v_mfma_f32_16x16x32_bf16 v[52:55], v[172:175], v[188:191], v[52:55]
	v_mfma_f32_16x16x32_bf16 v[48:51], v[180:183], v[188:191], v[48:51]
	v_mfma_f32_16x16x32_bf16 v[36:39], v[172:175], v[196:199], v[36:39]
	v_mfma_f32_16x16x32_bf16 v[32:35], v[180:183], v[196:199], v[32:35]
	v_mfma_f32_16x16x32_bf16 v[20:23], v[172:175], v[204:207], v[20:23]
	v_mfma_f32_16x16x32_bf16 v[16:19], v[180:183], v[204:207], v[16:19]
	v_mfma_f32_16x16x32_bf16 v[4:7], v[172:175], v[212:215], v[4:7]
	v_mfma_f32_16x16x32_bf16 v[0:3], v[180:183], v[212:215], v[0:3]
	s_setprio 0
	s_barrier
	s_add_i32 s66, 0, 0x18000
	v_add_u32_e32 v155, s66, v149
	s_add_i32 s67, 0, 0x1c000
	ds_read_b128 v[144:147], v155
	ds_read_b128 v[156:159], v155 offset:1024
	ds_read_b128 v[160:163], v155 offset:2048
	ds_read_b128 v[164:167], v155 offset:3072
	v_add_u32_e32 v155, s67, v149
	ds_read_b128 v[168:171], v155
	ds_read_b128 v[172:175], v155 offset:1024
	ds_read_b128 v[176:179], v155 offset:2048
	ds_read_b128 v[180:183], v155 offset:3072
	s_add_u32 s36, s36, 0x40000
	s_addc_u32 s37, s37, 0
	s_mov_b32 m0, s43
	v_lshl_add_u64 v[224:225], s[36:37], 0, v[134:135]
	ds_read_b128 v[184:187], v153 offset:32768
	ds_read_b128 v[188:191], v153 offset:33792
	ds_read_b128 v[192:195], v153 offset:34816
	ds_read_b128 v[196:199], v153 offset:35840
	ds_read_b128 v[200:203], v153 offset:36864
	ds_read_b128 v[204:207], v153 offset:37888
	ds_read_b128 v[208:211], v153 offset:38912
	ds_read_b128 v[212:215], v153 offset:39936
	global_load_lds_dwordx4 v[224:225], off
	v_lshl_add_u64 v[224:225], s[36:37], 0, v[130:131]
	s_mov_b32 m0, s46
	s_nop 0
	global_load_lds_dwordx4 v[224:225], off
	s_waitcnt vmcnt(8)
	s_waitcnt lgkmcnt(0)
	s_barrier
	s_setprio 1
	s_waitcnt lgkmcnt(0)
	v_mfma_f32_16x16x32_bf16 v[124:127], v[144:147], v[184:187], v[124:127]
	v_mfma_f32_16x16x32_bf16 v[120:123], v[160:163], v[184:187], v[120:123]
	v_mfma_f32_16x16x32_bf16 v[108:111], v[144:147], v[192:195], v[108:111]
	v_mfma_f32_16x16x32_bf16 v[104:107], v[160:163], v[192:195], v[104:107]
	v_mfma_f32_16x16x32_bf16 v[92:95], v[144:147], v[200:203], v[92:95]
	v_mfma_f32_16x16x32_bf16 v[88:91], v[160:163], v[200:203], v[88:91]
	v_mfma_f32_16x16x32_bf16 v[76:79], v[144:147], v[208:211], v[76:79]
	v_mfma_f32_16x16x32_bf16 v[72:75], v[160:163], v[208:211], v[72:75]
	v_mfma_f32_16x16x32_bf16 v[124:127], v[156:159], v[188:191], v[124:127]
	v_mfma_f32_16x16x32_bf16 v[120:123], v[164:167], v[188:191], v[120:123]
	v_mfma_f32_16x16x32_bf16 v[108:111], v[156:159], v[196:199], v[108:111]
	v_mfma_f32_16x16x32_bf16 v[104:107], v[164:167], v[196:199], v[104:107]
	v_mfma_f32_16x16x32_bf16 v[92:95], v[156:159], v[204:207], v[92:95]
	v_mfma_f32_16x16x32_bf16 v[88:91], v[164:167], v[204:207], v[88:91]
	v_mfma_f32_16x16x32_bf16 v[76:79], v[156:159], v[212:215], v[76:79]
	v_mfma_f32_16x16x32_bf16 v[72:75], v[164:167], v[212:215], v[72:75]
	s_setprio 0
	s_setprio 1
	v_mfma_f32_16x16x32_bf16 v[116:119], v[168:171], v[184:187], v[116:119]
	v_mfma_f32_16x16x32_bf16 v[112:115], v[176:179], v[184:187], v[112:115]
	v_mfma_f32_16x16x32_bf16 v[100:103], v[168:171], v[192:195], v[100:103]
	v_mfma_f32_16x16x32_bf16 v[96:99], v[176:179], v[192:195], v[96:99]
	v_mfma_f32_16x16x32_bf16 v[84:87], v[168:171], v[200:203], v[84:87]
	v_mfma_f32_16x16x32_bf16 v[80:83], v[176:179], v[200:203], v[80:83]
	v_mfma_f32_16x16x32_bf16 v[68:71], v[168:171], v[208:211], v[68:71]
	v_mfma_f32_16x16x32_bf16 v[64:67], v[176:179], v[208:211], v[64:67]
	v_mfma_f32_16x16x32_bf16 v[116:119], v[172:175], v[188:191], v[116:119]
	v_mfma_f32_16x16x32_bf16 v[112:115], v[180:183], v[188:191], v[112:115]
	v_mfma_f32_16x16x32_bf16 v[100:103], v[172:175], v[196:199], v[100:103]
	v_mfma_f32_16x16x32_bf16 v[96:99], v[180:183], v[196:199], v[96:99]
	v_mfma_f32_16x16x32_bf16 v[84:87], v[172:175], v[204:207], v[84:87]
	v_mfma_f32_16x16x32_bf16 v[80:83], v[180:183], v[204:207], v[80:83]
	v_mfma_f32_16x16x32_bf16 v[68:71], v[172:175], v[212:215], v[68:71]
	v_mfma_f32_16x16x32_bf16 v[64:67], v[180:183], v[212:215], v[64:67]
	s_setprio 0
	s_barrier
; #define PG8_STAGE(bufoff, gbase, voff) do { _Pragma("unroll") for (int _i = 0; _i < 2; ++_i) \
;         __builtin_amdgcn_global_load_lds((const unsigned*)((const char*)(gbase) + (voff)[_i]), (PG8_LAS unsigned*)(lds + (bufoff) + ldsw + _i * 8192), 16, 0, 0); } while (0)
; #define PG8_LDA(dst, b, h) do { _Pragma("unroll") for (int m = 0; m < 4; ++m) _Pragma("unroll") for (int k = 0; k < 2; ++k) dst[m][k] = *(const PG8_LAS bf16x8*)(lds + PG8_SA(b, h) + aoff + m * 2048 + k * 1024); } while (0)
; #define PG8_MMA(ai, bj, At, Bt) do { __builtin_amdgcn_s_setprio(1); _Pragma("unroll") for (int m = 0; m < 4; ++m) _Pragma("unroll") for (int n = 0; n < 2; ++n) _Pragma("unroll") for (int k = 0; k < 2; ++k) \
;         acc[ai][bj][m][n] = __builtin_amdgcn_mfma_f32_16x16x32_bf16(Bt[n][k], At[m][k], acc[ai][bj][m][n], 0, 0, 0); __builtin_amdgcn_s_setprio(0); } while (0)
; #define PG8_WAIT_V(n) asm volatile("s_waitcnt vmcnt(" #n ")" ::: "memory")
; #define PG8_WAIT_L(n) asm volatile("s_waitcnt lgkmcnt(" #n ")" ::: "memory")
; #define PG8_BAR __builtin_amdgcn_s_barrier()
; #define PG8_SCHED __builtin_amdgcn_sched_barrier(0)
; template <class Epi, class Sched, bool ALIGN_EPI = false, bool SP2 = false>
; __device__ __forceinline__ void gemm_phase(PG8_LAS unsigned char* lds, const Gemm g, const Sched& S, const Epi& E) {
;     ...
;             PG8_LDA(At, 1, 1); PG8_STAGE(PG8_SB(1, 0), b3, voffB); PG8_STAGE(PG8_SB(1, 1), b3 + hstep, voffB); PG8_STAGE(PG8_SA(1, 0), a3, voffA);
;             PG8_WAIT_V(8); PG8_WAIT_L(0); PG8_BAR; PG8_MMA(1, 0, At, B0); PG8_MMA(1, 1, At, B1); PG8_BAR; PG8_SCHED;
;     ...
;         if constexpr (ALIGN_EPI) { if (wr == 0) PG8_BAR; }
	s_add_i32 s36, s66, s39
	v_lshl_add_u64 v[216:217], v[216:217], 0, s[14:15]
	s_mov_b32 m0, s36
	ds_read_b128 v[184:187], v153 offset:49152
	ds_read_b128 v[188:191], v153 offset:50176
	ds_read_b128 v[192:195], v153 offset:51200
	ds_read_b128 v[196:199], v153 offset:52224
	ds_read_b128 v[200:203], v153 offset:53248
	ds_read_b128 v[204:207], v153 offset:54272
	ds_read_b128 v[208:211], v153 offset:55296
	ds_read_b128 v[212:215], v153 offset:56320
	global_load_lds_dwordx4 v[216:217], off
	s_add_i32 m0, s36, 0x2000
	s_add_u32 s34, s34, 0x40080
	v_lshl_add_u64 v[216:217], v[218:219], 0, s[14:15]
	s_addc_u32 s35, s35, 0
	s_add_i32 s36, s67, s39
	global_load_lds_dwordx4 v[216:217], off
	v_lshl_add_u64 v[216:217], s[34:35], 0, v[132:133]
	s_mov_b32 m0, s36
	s_nop 0
	global_load_lds_dwordx4 v[216:217], off
	v_lshl_add_u64 v[216:217], s[34:35], 0, v[128:129]
	s_add_i32 m0, s36, 0x2000
	s_nop 0
	global_load_lds_dwordx4 v[216:217], off
	s_waitcnt vmcnt(6)
	s_waitcnt lgkmcnt(0)
	s_barrier
	s_setprio 1
	s_waitcnt lgkmcnt(0)
	v_mfma_f32_16x16x32_bf16 v[60:63], v[144:147], v[184:187], v[60:63]
	v_mfma_f32_16x16x32_bf16 v[56:59], v[160:163], v[184:187], v[56:59]
	v_mfma_f32_16x16x32_bf16 v[44:47], v[144:147], v[192:195], v[44:47]
	v_mfma_f32_16x16x32_bf16 v[40:43], v[160:163], v[192:195], v[40:43]
	v_mfma_f32_16x16x32_bf16 v[28:31], v[144:147], v[200:203], v[28:31]
	v_mfma_f32_16x16x32_bf16 v[24:27], v[160:163], v[200:203], v[24:27]
	v_mfma_f32_16x16x32_bf16 v[12:15], v[144:147], v[208:211], v[12:15]
	v_mfma_f32_16x16x32_bf16 v[8:11], v[160:163], v[208:211], v[8:11]
	v_mfma_f32_16x16x32_bf16 v[60:63], v[156:159], v[188:191], v[60:63]
	v_mfma_f32_16x16x32_bf16 v[56:59], v[164:167], v[188:191], v[56:59]
	v_mfma_f32_16x16x32_bf16 v[44:47], v[156:159], v[196:199], v[44:47]
	v_mfma_f32_16x16x32_bf16 v[40:43], v[164:167], v[196:199], v[40:43]
	v_mfma_f32_16x16x32_bf16 v[28:31], v[156:159], v[204:207], v[28:31]
	v_mfma_f32_16x16x32_bf16 v[24:27], v[164:167], v[204:207], v[24:27]
	v_mfma_f32_16x16x32_bf16 v[12:15], v[156:159], v[212:215], v[12:15]
	v_mfma_f32_16x16x32_bf16 v[8:11], v[164:167], v[212:215], v[8:11]
	s_setprio 0
	v_lshl_add_u64 v[216:217], v[220:221], 0, s[14:15]
	s_mov_b32 m0, s49
	s_nop 0
	global_load_lds_dwordx4 v[216:217], off
	v_lshl_add_u64 v[216:217], v[222:223], 0, s[14:15]
	s_mov_b32 m0, s50
	s_nop 0
	global_load_lds_dwordx4 v[216:217], off
	s_setprio 1
	v_mfma_f32_16x16x32_bf16 v[52:55], v[168:171], v[184:187], v[52:55]
	v_mfma_f32_16x16x32_bf16 v[48:51], v[176:179], v[184:187], v[48:51]
	v_mfma_f32_16x16x32_bf16 v[36:39], v[168:171], v[192:195], v[36:39]
	v_mfma_f32_16x16x32_bf16 v[32:35], v[176:179], v[192:195], v[32:35]
	v_mfma_f32_16x16x32_bf16 v[20:23], v[168:171], v[200:203], v[20:23]
	v_mfma_f32_16x16x32_bf16 v[16:19], v[176:179], v[200:203], v[16:19]
	v_mfma_f32_16x16x32_bf16 v[4:7], v[168:171], v[208:211], v[4:7]
	v_mfma_f32_16x16x32_bf16 v[0:3], v[176:179], v[208:211], v[0:3]
	v_mfma_f32_16x16x32_bf16 v[52:55], v[172:175], v[188:191], v[52:55]
	v_mfma_f32_16x16x32_bf16 v[48:51], v[180:183], v[188:191], v[48:51]
	v_mfma_f32_16x16x32_bf16 v[36:39], v[172:175], v[196:199], v[36:39]
	v_mfma_f32_16x16x32_bf16 v[32:35], v[180:183], v[196:199], v[32:35]
	v_mfma_f32_16x16x32_bf16 v[20:23], v[172:175], v[204:207], v[20:23]
	v_mfma_f32_16x16x32_bf16 v[16:19], v[180:183], v[204:207], v[16:19]
	v_mfma_f32_16x16x32_bf16 v[4:7], v[172:175], v[212:215], v[4:7]
	v_mfma_f32_16x16x32_bf16 v[0:3], v[180:183], v[212:215], v[0:3]
	s_setprio 0
	s_barrier
	s_add_i32 s65, s65, 2
	s_add_u32 s30, s30, 0x100
	s_addc_u32 s31, s31, 0
	s_add_u32 s63, s63, 0x100
	s_addc_u32 s64, s64, 0
	s_cmp_gt_u32 s65, 13
	s_cbranch_scc0 .LBB0_1540
	s_and_b64 vcc, exec, s[16:17]
	s_cbranch_vccz .LBB0_1543
	s_barrier

; #define PG8_STAGE(bufoff, gbase, voff) do { _Pragma("unroll") for (int _i = 0; _i < 2; ++_i) \
;         __builtin_amdgcn_global_load_lds((const unsigned*)((const char*)(gbase) + (voff)[_i]), (PG8_LAS unsigned*)(lds + (bufoff) + ldsw + _i * 8192), 16, 0, 0); } while (0)
; #define PG8_LDA(dst, b, h) do { _Pragma("unroll") for (int m = 0; m < 4; ++m) _Pragma("unroll") for (int k = 0; k < 2; ++k) dst[m][k] = *(const PG8_LAS bf16x8*)(lds + PG8_SA(b, h) + aoff + m * 2048 + k * 1024); } while (0)
; #define PG8_LDB(dst, b, h) do { _Pragma("unroll") for (int n = 0; n < 2; ++n) _Pragma("unroll") for (int k = 0; k < 2; ++k) dst[n][k] = *(const PG8_LAS bf16x8*)(lds + PG8_SB(b, h) + boff + n * 2048 + k * 1024); } while (0)
; #define PG8_MMA(ai, bj, At, Bt) do { __builtin_amdgcn_s_setprio(1); _Pragma("unroll") for (int m = 0; m < 4; ++m) _Pragma("unroll") for (int n = 0; n < 2; ++n) _Pragma("unroll") for (int k = 0; k < 2; ++k) \
;         acc[ai][bj][m][n] = __builtin_amdgcn_mfma_f32_16x16x32_bf16(Bt[n][k], At[m][k], acc[ai][bj][m][n], 0, 0, 0); __builtin_amdgcn_s_setprio(0); } while (0)
; #define PG8_WAIT_V(n) asm volatile("s_waitcnt vmcnt(" #n ")" ::: "memory")
; #define PG8_WAIT_L(n) asm volatile("s_waitcnt lgkmcnt(" #n ")" ::: "memory")
; #define PG8_BAR __builtin_amdgcn_s_barrier()
; #define PG8_SCHED __builtin_amdgcn_sched_barrier(0)
; template <class Epi, class Sched, bool ALIGN_EPI = false, bool SP2 = false>
; __device__ __forceinline__ void gemm_phase(PG8_LAS unsigned char* lds, const Gemm g, const Sched& S, const Epi& E) {
;     ...
;             PG8_LDB(B0, 0, 0); PG8_LDB(B1, 0, 1); PG8_SCHED; PG8_LDA(At, 0, 0); PG8_STAGE(PG8_SA(1, 1), a1 + hstep, voffA);
;             PG8_WAIT_V(8); PG8_WAIT_L(0); PG8_BAR; PG8_MMA(0, 0, At, B0); PG8_MMA(0, 1, At, B1); PG8_BAR; PG8_SCHED;
;             PG8_LDA(At, 0, 1); PG8_STAGE(PG8_SB(0, 0), b2, voffB); PG8_STAGE(PG8_SB(0, 1), b2 + hstep, voffB); PG8_STAGE(PG8_SA(0, 0), a2, voffA);
;             PG8_WAIT_V(8); PG8_WAIT_L(0); PG8_BAR; PG8_MMA(1, 0, At, B0); PG8_MMA(1, 1, At, B1); PG8_BAR; PG8_SCHED;
.LBB0_2136:
	ds_read_b128 v[152:155], v149
	ds_read_b128 v[156:159], v149 offset:1024
	ds_read_b128 v[160:163], v149 offset:2048
	ds_read_b128 v[164:167], v149 offset:3072
	ds_read_b128 v[168:171], v150
	ds_read_b128 v[172:175], v150 offset:1024
	ds_read_b128 v[176:179], v150 offset:2048
	ds_read_b128 v[180:183], v150 offset:3072
	s_add_u32 s30, s28, 0xfff00080
	s_addc_u32 s31, s29, -1
	s_cmp_eq_u32 s68, 60
	s_cselect_b32 s35, s21, s31
	s_cselect_b32 s34, s64, s30
	s_cselect_b32 s31, s19, s67
	s_cselect_b32 s30, s65, s66
	v_lshl_add_u64 v[144:145], s[28:29], 0, v[136:137]
	s_add_i32 m0, s27, 0xc000
	ds_read_b128 v[184:187], v151
	ds_read_b128 v[188:191], v151 offset:1024
	ds_read_b128 v[192:195], v151 offset:2048
	ds_read_b128 v[196:199], v151 offset:3072
	ds_read_b128 v[200:203], v151 offset:4096
	ds_read_b128 v[204:207], v151 offset:5120
	ds_read_b128 v[208:211], v151 offset:6144
	ds_read_b128 v[212:215], v151 offset:7168
	global_load_lds_dwordx4 v[144:145], off
	v_lshl_add_u64 v[144:145], s[28:29], 0, v[138:139]
	s_add_i32 m0, s27, 0xe000
	s_nop 0
	global_load_lds_dwordx4 v[144:145], off
	s_waitcnt vmcnt(8)
	s_waitcnt lgkmcnt(0)
	s_barrier
	s_setprio 1
	s_waitcnt lgkmcnt(0)
	v_mfma_f32_16x16x32_bf16 v[124:127], v[152:155], v[184:187], v[124:127]
	v_mfma_f32_16x16x32_bf16 v[120:123], v[160:163], v[184:187], v[120:123]
	v_mfma_f32_16x16x32_bf16 v[108:111], v[152:155], v[192:195], v[108:111]
	v_mfma_f32_16x16x32_bf16 v[104:107], v[160:163], v[192:195], v[104:107]
	v_mfma_f32_16x16x32_bf16 v[92:95], v[152:155], v[200:203], v[92:95]
	v_mfma_f32_16x16x32_bf16 v[88:91], v[160:163], v[200:203], v[88:91]
	v_mfma_f32_16x16x32_bf16 v[76:79], v[152:155], v[208:211], v[76:79]
	v_mfma_f32_16x16x32_bf16 v[72:75], v[160:163], v[208:211], v[72:75]
	v_mfma_f32_16x16x32_bf16 v[124:127], v[156:159], v[188:191], v[124:127]
	v_mfma_f32_16x16x32_bf16 v[120:123], v[164:167], v[188:191], v[120:123]
	v_mfma_f32_16x16x32_bf16 v[108:111], v[156:159], v[196:199], v[108:111]
	v_mfma_f32_16x16x32_bf16 v[104:107], v[164:167], v[196:199], v[104:107]
	v_mfma_f32_16x16x32_bf16 v[92:95], v[156:159], v[204:207], v[92:95]
	v_mfma_f32_16x16x32_bf16 v[88:91], v[164:167], v[204:207], v[88:91]
	v_mfma_f32_16x16x32_bf16 v[76:79], v[156:159], v[212:215], v[76:79]
	v_mfma_f32_16x16x32_bf16 v[72:75], v[164:167], v[212:215], v[72:75]
	s_setprio 0
	s_setprio 1
	v_mfma_f32_16x16x32_bf16 v[116:119], v[168:171], v[184:187], v[116:119]
	v_mfma_f32_16x16x32_bf16 v[112:115], v[176:179], v[184:187], v[112:115]
	v_mfma_f32_16x16x32_bf16 v[100:103], v[168:171], v[192:195], v[100:103]
	v_mfma_f32_16x16x32_bf16 v[96:99], v[176:179], v[192:195], v[96:99]
	v_mfma_f32_16x16x32_bf16 v[84:87], v[168:171], v[200:203], v[84:87]
	v_mfma_f32_16x16x32_bf16 v[80:83], v[176:179], v[200:203], v[80:83]
	v_mfma_f32_16x16x32_bf16 v[68:71], v[168:171], v[208:211], v[68:71]
	v_mfma_f32_16x16x32_bf16 v[64:67], v[176:179], v[208:211], v[64:67]
	v_mfma_f32_16x16x32_bf16 v[116:119], v[172:175], v[188:191], v[116:119]
	v_mfma_f32_16x16x32_bf16 v[112:115], v[180:183], v[188:191], v[112:115]
	v_mfma_f32_16x16x32_bf16 v[100:103], v[172:175], v[196:199], v[100:103]
	v_mfma_f32_16x16x32_bf16 v[96:99], v[180:183], v[196:199], v[96:99]
	v_mfma_f32_16x16x32_bf16 v[84:87], v[172:175], v[204:207], v[84:87]
	v_mfma_f32_16x16x32_bf16 v[80:83], v[180:183], v[204:207], v[80:83]
	v_mfma_f32_16x16x32_bf16 v[68:71], v[172:175], v[212:215], v[68:71]
	v_mfma_f32_16x16x32_bf16 v[64:67], v[180:183], v[212:215], v[64:67]
	s_setprio 0
	s_barrier
	s_add_i32 s69, s51, s39
	v_lshl_add_u64 v[144:145], s[30:31], 0, v[132:133]
	s_mov_b32 m0, s69
	ds_read_b128 v[184:187], v151 offset:16384
	ds_read_b128 v[188:191], v151 offset:17408
	ds_read_b128 v[192:195], v151 offset:18432
	ds_read_b128 v[196:199], v151 offset:19456
	ds_read_b128 v[200:203], v151 offset:20480
	ds_read_b128 v[204:207], v151 offset:21504
	ds_read_b128 v[208:211], v151 offset:22528
	ds_read_b128 v[212:215], v151 offset:23552
	global_load_lds_dwordx4 v[144:145], off
	s_add_i32 m0, s69, 0x2000
	s_add_u32 s70, s30, 0x100000
	v_lshl_add_u64 v[216:217], s[30:31], 0, v[128:129]
	s_addc_u32 s71, s31, 0
	s_add_i32 s69, s52, s39
	global_load_lds_dwordx4 v[216:217], off
	v_lshl_add_u64 v[218:219], s[70:71], 0, v[132:133]
	s_mov_b32 m0, s69
	v_lshl_add_u64 v[220:221], s[34:35], 0, v[130:131]
	global_load_lds_dwordx4 v[218:219], off
	v_lshl_add_u64 v[218:219], s[70:71], 0, v[128:129]
	s_add_i32 m0, s69, 0x2000
	s_nop 0
	global_load_lds_dwordx4 v[218:219], off
	s_waitcnt vmcnt(6)
	s_waitcnt lgkmcnt(0)
	s_barrier
; #define PG8_STAGE(bufoff, gbase, voff) do { _Pragma("unroll") for (int _i = 0; _i < 2; ++_i) \
;         __builtin_amdgcn_global_load_lds((const unsigned*)((const char*)(gbase) + (voff)[_i]), (PG8_LAS unsigned*)(lds + (bufoff) + ldsw + _i * 8192), 16, 0, 0); } while (0)
; #define PG8_LDA(dst, b, h) do { _Pragma("unroll") for (int m = 0; m < 4; ++m) _Pragma("unroll") for (int k = 0; k < 2; ++k) dst[m][k] = *(const PG8_LAS bf16x8*)(lds + PG8_SA(b, h) + aoff + m * 2048 + k * 1024); } while (0)
; #define PG8_LDB(dst, b, h) do { _Pragma("unroll") for (int n = 0; n < 2; ++n) _Pragma("unroll") for (int k = 0; k < 2; ++k) dst[n][k] = *(const PG8_LAS bf16x8*)(lds + PG8_SB(b, h) + boff + n * 2048 + k * 1024); } while (0)
; #define PG8_MMA(ai, bj, At, Bt) do { __builtin_amdgcn_s_setprio(1); _Pragma("unroll") for (int m = 0; m < 4; ++m) _Pragma("unroll") for (int n = 0; n < 2; ++n) _Pragma("unroll") for (int k = 0; k < 2; ++k) \
;         acc[ai][bj][m][n] = __builtin_amdgcn_mfma_f32_16x16x32_bf16(Bt[n][k], At[m][k], acc[ai][bj][m][n], 0, 0, 0); __builtin_amdgcn_s_setprio(0); } while (0)
; #define PG8_WAIT_V(n) asm volatile("s_waitcnt vmcnt(" #n ")" ::: "memory")
; #define PG8_WAIT_L(n) asm volatile("s_waitcnt lgkmcnt(" #n ")" ::: "memory")
; #define PG8_BAR __builtin_amdgcn_s_barrier()
; #define PG8_SCHED __builtin_amdgcn_sched_barrier(0)
; template <class Epi, class Sched, bool ALIGN_EPI = false, bool SP2 = false>
; __device__ __forceinline__ void gemm_phase(PG8_LAS unsigned char* lds, const Gemm g, const Sched& S, const Epi& E) {
;     ...
;             PG8_WAIT_V(8); PG8_WAIT_L(0); PG8_BAR; PG8_MMA(1, 0, At, B0); PG8_MMA(1, 1, At, B1); PG8_BAR; PG8_SCHED;
;             PG8_LDB(B0, 1, 0); PG8_LDB(B1, 1, 1); PG8_SCHED; PG8_LDA(At, 1, 0); PG8_STAGE(PG8_SA(0, 1), a2 + hstep, voffA);
;             PG8_WAIT_V(8); PG8_WAIT_L(0); PG8_BAR; PG8_MMA(0, 0, At, B0); PG8_MMA(0, 1, At, B1); PG8_BAR; PG8_SCHED;
	s_setprio 1
	s_waitcnt lgkmcnt(0)
	v_mfma_f32_16x16x32_bf16 v[60:63], v[152:155], v[184:187], v[60:63]
	v_mfma_f32_16x16x32_bf16 v[56:59], v[160:163], v[184:187], v[56:59]
	v_mfma_f32_16x16x32_bf16 v[44:47], v[152:155], v[192:195], v[44:47]
	v_mfma_f32_16x16x32_bf16 v[40:43], v[160:163], v[192:195], v[40:43]
	v_mfma_f32_16x16x32_bf16 v[28:31], v[152:155], v[200:203], v[28:31]
	v_mfma_f32_16x16x32_bf16 v[24:27], v[160:163], v[200:203], v[24:27]
	v_mfma_f32_16x16x32_bf16 v[12:15], v[152:155], v[208:211], v[12:15]
	v_mfma_f32_16x16x32_bf16 v[8:11], v[160:163], v[208:211], v[8:11]
	v_mfma_f32_16x16x32_bf16 v[60:63], v[156:159], v[188:191], v[60:63]
	v_mfma_f32_16x16x32_bf16 v[56:59], v[164:167], v[188:191], v[56:59]
	v_mfma_f32_16x16x32_bf16 v[44:47], v[156:159], v[196:199], v[44:47]
	v_mfma_f32_16x16x32_bf16 v[40:43], v[164:167], v[196:199], v[40:43]
	v_mfma_f32_16x16x32_bf16 v[28:31], v[156:159], v[204:207], v[28:31]
	v_mfma_f32_16x16x32_bf16 v[24:27], v[164:167], v[204:207], v[24:27]
	v_mfma_f32_16x16x32_bf16 v[12:15], v[156:159], v[212:215], v[12:15]
	v_mfma_f32_16x16x32_bf16 v[8:11], v[164:167], v[212:215], v[8:11]
	s_setprio 0
	v_lshl_add_u64 v[218:219], s[34:35], 0, v[134:135]
	s_mov_b32 m0, s27
	s_nop 0
	global_load_lds_dwordx4 v[218:219], off
	s_mov_b32 m0, s42
	s_nop 0
	global_load_lds_dwordx4 v[220:221], off
	s_setprio 1
	v_mfma_f32_16x16x32_bf16 v[52:55], v[168:171], v[184:187], v[52:55]
	v_mfma_f32_16x16x32_bf16 v[48:51], v[176:179], v[184:187], v[48:51]
	v_mfma_f32_16x16x32_bf16 v[36:39], v[168:171], v[192:195], v[36:39]
	v_mfma_f32_16x16x32_bf16 v[32:35], v[176:179], v[192:195], v[32:35]
	v_mfma_f32_16x16x32_bf16 v[20:23], v[168:171], v[200:203], v[20:23]
	v_mfma_f32_16x16x32_bf16 v[16:19], v[176:179], v[200:203], v[16:19]
	v_mfma_f32_16x16x32_bf16 v[4:7], v[168:171], v[208:211], v[4:7]
	v_mfma_f32_16x16x32_bf16 v[0:3], v[176:179], v[208:211], v[0:3]
	v_mfma_f32_16x16x32_bf16 v[52:55], v[172:175], v[188:191], v[52:55]
	v_mfma_f32_16x16x32_bf16 v[48:51], v[180:183], v[188:191], v[48:51]
	v_mfma_f32_16x16x32_bf16 v[36:39], v[172:175], v[196:199], v[36:39]
	v_mfma_f32_16x16x32_bf16 v[32:35], v[180:183], v[196:199], v[32:35]
	v_mfma_f32_16x16x32_bf16 v[20:23], v[172:175], v[204:207], v[20:23]
	v_mfma_f32_16x16x32_bf16 v[16:19], v[180:183], v[204:207], v[16:19]
	v_mfma_f32_16x16x32_bf16 v[4:7], v[172:175], v[212:215], v[4:7]
	v_mfma_f32_16x16x32_bf16 v[0:3], v[180:183], v[212:215], v[0:3]
	s_setprio 0
	s_barrier
	s_add_i32 s69, 0, 0x18000
	s_add_i32 s70, 0, 0x1c000
	v_add_u32_e32 v164, s69, v147
	v_add_u32_e32 v180, s70, v147
	ds_read_b128 v[152:155], v164
	ds_read_b128 v[156:159], v164 offset:1024
	ds_read_b128 v[160:163], v164 offset:2048
	ds_read_b128 v[164:167], v164 offset:3072
	ds_read_b128 v[168:171], v180
	ds_read_b128 v[172:175], v180 offset:1024
	ds_read_b128 v[176:179], v180 offset:2048
	ds_read_b128 v[180:183], v180 offset:3072
	s_add_u32 s34, s34, 0x100000
	s_addc_u32 s35, s35, 0
	s_mov_b32 m0, s43
	v_lshl_add_u64 v[222:223], s[34:35], 0, v[134:135]
	ds_read_b128 v[184:187], v151 offset:32768
	ds_read_b128 v[188:191], v151 offset:33792
	ds_read_b128 v[192:195], v151 offset:34816
	ds_read_b128 v[196:199], v151 offset:35840
	ds_read_b128 v[200:203], v151 offset:36864
	ds_read_b128 v[204:207], v151 offset:37888
	ds_read_b128 v[208:211], v151 offset:38912
	ds_read_b128 v[212:215], v151 offset:39936
	global_load_lds_dwordx4 v[222:223], off
	v_lshl_add_u64 v[222:223], s[34:35], 0, v[130:131]
	s_mov_b32 m0, s46
	s_nop 0
	global_load_lds_dwordx4 v[222:223], off
	s_waitcnt vmcnt(8)
	s_waitcnt lgkmcnt(0)
	s_barrier
	s_setprio 1
	s_waitcnt lgkmcnt(0)
	v_mfma_f32_16x16x32_bf16 v[124:127], v[152:155], v[184:187], v[124:127]
	v_mfma_f32_16x16x32_bf16 v[120:123], v[160:163], v[184:187], v[120:123]
	v_mfma_f32_16x16x32_bf16 v[108:111], v[152:155], v[192:195], v[108:111]
	v_mfma_f32_16x16x32_bf16 v[104:107], v[160:163], v[192:195], v[104:107]
	v_mfma_f32_16x16x32_bf16 v[92:95], v[152:155], v[200:203], v[92:95]
	v_mfma_f32_16x16x32_bf16 v[88:91], v[160:163], v[200:203], v[88:91]
	v_mfma_f32_16x16x32_bf16 v[76:79], v[152:155], v[208:211], v[76:79]
	v_mfma_f32_16x16x32_bf16 v[72:75], v[160:163], v[208:211], v[72:75]
	v_mfma_f32_16x16x32_bf16 v[124:127], v[156:159], v[188:191], v[124:127]
	v_mfma_f32_16x16x32_bf16 v[120:123], v[164:167], v[188:191], v[120:123]
	v_mfma_f32_16x16x32_bf16 v[108:111], v[156:159], v[196:199], v[108:111]
	v_mfma_f32_16x16x32_bf16 v[104:107], v[164:167], v[196:199], v[104:107]
	v_mfma_f32_16x16x32_bf16 v[92:95], v[156:159], v[204:207], v[92:95]
	v_mfma_f32_16x16x32_bf16 v[88:91], v[164:167], v[204:207], v[88:91]
	v_mfma_f32_16x16x32_bf16 v[76:79], v[156:159], v[212:215], v[76:79]
	v_mfma_f32_16x16x32_bf16 v[72:75], v[164:167], v[212:215], v[72:75]
	s_setprio 0
	s_setprio 1
	v_mfma_f32_16x16x32_bf16 v[116:119], v[168:171], v[184:187], v[116:119]
	v_mfma_f32_16x16x32_bf16 v[112:115], v[176:179], v[184:187], v[112:115]
	v_mfma_f32_16x16x32_bf16 v[100:103], v[168:171], v[192:195], v[100:103]
	v_mfma_f32_16x16x32_bf16 v[96:99], v[176:179], v[192:195], v[96:99]
	v_mfma_f32_16x16x32_bf16 v[84:87], v[168:171], v[200:203], v[84:87]
	v_mfma_f32_16x16x32_bf16 v[80:83], v[176:179], v[200:203], v[80:83]
	v_mfma_f32_16x16x32_bf16 v[68:71], v[168:171], v[208:211], v[68:71]
	v_mfma_f32_16x16x32_bf16 v[64:67], v[176:179], v[208:211], v[64:67]
	v_mfma_f32_16x16x32_bf16 v[116:119], v[172:175], v[188:191], v[116:119]
	v_mfma_f32_16x16x32_bf16 v[112:115], v[180:183], v[188:191], v[112:115]
	v_mfma_f32_16x16x32_bf16 v[100:103], v[172:175], v[196:199], v[100:103]
	v_mfma_f32_16x16x32_bf16 v[96:99], v[180:183], v[196:199], v[96:99]
	v_mfma_f32_16x16x32_bf16 v[84:87], v[172:175], v[204:207], v[84:87]
	v_mfma_f32_16x16x32_bf16 v[80:83], v[180:183], v[204:207], v[80:83]
	v_mfma_f32_16x16x32_bf16 v[68:71], v[172:175], v[212:215], v[68:71]
	v_mfma_f32_16x16x32_bf16 v[64:67], v[180:183], v[212:215], v[64:67]
	s_setprio 0
	s_barrier
; #define PG8_STAGE(bufoff, gbase, voff) do { _Pragma("unroll") for (int _i = 0; _i < 2; ++_i) \
;         __builtin_amdgcn_global_load_lds((const unsigned*)((const char*)(gbase) + (voff)[_i]), (PG8_LAS unsigned*)(lds + (bufoff) + ldsw + _i * 8192), 16, 0, 0); } while (0)
; #define PG8_LDA(dst, b, h) do { _Pragma("unroll") for (int m = 0; m < 4; ++m) _Pragma("unroll") for (int k = 0; k < 2; ++k) dst[m][k] = *(const PG8_LAS bf16x8*)(lds + PG8_SA(b, h) + aoff + m * 2048 + k * 1024); } while (0)
; #define PG8_MMA(ai, bj, At, Bt) do { __builtin_amdgcn_s_setprio(1); _Pragma("unroll") for (int m = 0; m < 4; ++m) _Pragma("unroll") for (int n = 0; n < 2; ++n) _Pragma("unroll") for (int k = 0; k < 2; ++k) \
;         acc[ai][bj][m][n] = __builtin_amdgcn_mfma_f32_16x16x32_bf16(Bt[n][k], At[m][k], acc[ai][bj][m][n], 0, 0, 0); __builtin_amdgcn_s_setprio(0); } while (0)
; #define PG8_WAIT_V(n) asm volatile("s_waitcnt vmcnt(" #n ")" ::: "memory")
; #define PG8_WAIT_L(n) asm volatile("s_waitcnt lgkmcnt(" #n ")" ::: "memory")
; #define PG8_BAR __builtin_amdgcn_s_barrier()
; #define PG8_SCHED __builtin_amdgcn_sched_barrier(0)
; template <class Epi, class Sched, bool ALIGN_EPI = false, bool SP2 = false>
; __device__ __forceinline__ void gemm_phase(PG8_LAS unsigned char* lds, const Gemm g, const Sched& S, const Epi& E) {
;     ...
;             PG8_LDA(At, 1, 1); PG8_STAGE(PG8_SB(1, 0), b3, voffB); PG8_STAGE(PG8_SB(1, 1), b3 + hstep, voffB); PG8_STAGE(PG8_SA(1, 0), a3, voffA);
;             PG8_WAIT_V(8); PG8_WAIT_L(0); PG8_BAR; PG8_MMA(1, 0, At, B0); PG8_MMA(1, 1, At, B1); PG8_BAR; PG8_SCHED;
;     ...
;         if constexpr (ALIGN_EPI) { if (wr == 0) PG8_BAR; }
	s_add_i32 s34, s69, s39
	v_lshl_add_u64 v[144:145], v[144:145], 0, s[6:7]
	s_mov_b32 m0, s34
	ds_read_b128 v[184:187], v151 offset:49152
	ds_read_b128 v[188:191], v151 offset:50176
	ds_read_b128 v[192:195], v151 offset:51200
	ds_read_b128 v[196:199], v151 offset:52224
	ds_read_b128 v[200:203], v151 offset:53248
	ds_read_b128 v[204:207], v151 offset:54272
	ds_read_b128 v[208:211], v151 offset:55296
	ds_read_b128 v[212:215], v151 offset:56320
	global_load_lds_dwordx4 v[144:145], off
	s_add_i32 m0, s34, 0x2000
	s_add_u32 s30, s30, 0x100080
	v_lshl_add_u64 v[144:145], v[216:217], 0, s[6:7]
	s_addc_u32 s31, s31, 0
	s_add_i32 s34, s70, s39
	global_load_lds_dwordx4 v[144:145], off
	v_lshl_add_u64 v[144:145], s[30:31], 0, v[132:133]
	s_mov_b32 m0, s34
	s_nop 0
	global_load_lds_dwordx4 v[144:145], off
	v_lshl_add_u64 v[144:145], s[30:31], 0, v[128:129]
	s_add_i32 m0, s34, 0x2000
	s_nop 0
	global_load_lds_dwordx4 v[144:145], off
	s_waitcnt vmcnt(6)
	s_waitcnt lgkmcnt(0)
	s_barrier
	s_setprio 1
	s_waitcnt lgkmcnt(0)
	v_mfma_f32_16x16x32_bf16 v[60:63], v[152:155], v[184:187], v[60:63]
	v_mfma_f32_16x16x32_bf16 v[56:59], v[160:163], v[184:187], v[56:59]
	v_mfma_f32_16x16x32_bf16 v[44:47], v[152:155], v[192:195], v[44:47]
	v_mfma_f32_16x16x32_bf16 v[40:43], v[160:163], v[192:195], v[40:43]
	v_mfma_f32_16x16x32_bf16 v[28:31], v[152:155], v[200:203], v[28:31]
	v_mfma_f32_16x16x32_bf16 v[24:27], v[160:163], v[200:203], v[24:27]
	v_mfma_f32_16x16x32_bf16 v[12:15], v[152:155], v[208:211], v[12:15]
	v_mfma_f32_16x16x32_bf16 v[8:11], v[160:163], v[208:211], v[8:11]
	v_mfma_f32_16x16x32_bf16 v[60:63], v[156:159], v[188:191], v[60:63]
	v_mfma_f32_16x16x32_bf16 v[56:59], v[164:167], v[188:191], v[56:59]
	v_mfma_f32_16x16x32_bf16 v[44:47], v[156:159], v[196:199], v[44:47]
	v_mfma_f32_16x16x32_bf16 v[40:43], v[164:167], v[196:199], v[40:43]
	v_mfma_f32_16x16x32_bf16 v[28:31], v[156:159], v[204:207], v[28:31]
	v_mfma_f32_16x16x32_bf16 v[24:27], v[164:167], v[204:207], v[24:27]
	v_mfma_f32_16x16x32_bf16 v[12:15], v[156:159], v[212:215], v[12:15]
	v_mfma_f32_16x16x32_bf16 v[8:11], v[164:167], v[212:215], v[8:11]
	s_setprio 0
	v_lshl_add_u64 v[144:145], v[218:219], 0, s[6:7]
	s_mov_b32 m0, s48
	s_nop 0
	global_load_lds_dwordx4 v[144:145], off
	v_lshl_add_u64 v[144:145], v[220:221], 0, s[6:7]
	s_mov_b32 m0, s49
	s_nop 0
	global_load_lds_dwordx4 v[144:145], off
	s_setprio 1
	v_mfma_f32_16x16x32_bf16 v[52:55], v[168:171], v[184:187], v[52:55]
	v_mfma_f32_16x16x32_bf16 v[48:51], v[176:179], v[184:187], v[48:51]
	v_mfma_f32_16x16x32_bf16 v[36:39], v[168:171], v[192:195], v[36:39]
	v_mfma_f32_16x16x32_bf16 v[32:35], v[176:179], v[192:195], v[32:35]
	v_mfma_f32_16x16x32_bf16 v[20:23], v[168:171], v[200:203], v[20:23]
	v_mfma_f32_16x16x32_bf16 v[16:19], v[176:179], v[200:203], v[16:19]
	v_mfma_f32_16x16x32_bf16 v[4:7], v[168:171], v[208:211], v[4:7]
	v_mfma_f32_16x16x32_bf16 v[0:3], v[176:179], v[208:211], v[0:3]
	v_mfma_f32_16x16x32_bf16 v[52:55], v[172:175], v[188:191], v[52:55]
	v_mfma_f32_16x16x32_bf16 v[48:51], v[180:183], v[188:191], v[48:51]
	v_mfma_f32_16x16x32_bf16 v[36:39], v[172:175], v[196:199], v[36:39]
	v_mfma_f32_16x16x32_bf16 v[32:35], v[180:183], v[196:199], v[32:35]
	v_mfma_f32_16x16x32_bf16 v[20:23], v[172:175], v[204:207], v[20:23]
	v_mfma_f32_16x16x32_bf16 v[16:19], v[180:183], v[204:207], v[16:19]
	v_mfma_f32_16x16x32_bf16 v[4:7], v[172:175], v[212:215], v[4:7]
	v_mfma_f32_16x16x32_bf16 v[0:3], v[180:183], v[212:215], v[0:3]
	s_setprio 0
	s_barrier
	s_add_i32 s68, s68, 2
	s_add_u32 s28, s28, 0x100
	s_addc_u32 s29, s29, 0
	s_add_u32 s66, s66, 0x100
	s_addc_u32 s67, s67, 0
	s_cmp_gt_u32 s68, 61
	s_cbranch_scc0 .LBB0_2136
	s_and_b64 vcc, exec, s[8:9]
	s_cbranch_vccz .LBB0_2139
	s_barrier
